# phases 3 and 12: 4 barrier intervals per K-tile (32 MFMA each) + static priority for waves 4-7; phases 10, 13 static priority
# speedup vs baseline: 1.0045x; 1.0045x over previous
;     __device__ __forceinline__ bool next(int i, Unit& u) const { if (i != 0 || c >= n) return false; u.pm = 0; u.pn = c; u.kt0 = 0; u.nkt = ntk; u.piece = -1; return true; }
; #define PG8_WAIT_V(n) asm volatile("s_waitcnt vmcnt(" #n ")" ::: "memory")
; #define PG8_BAR __builtin_amdgcn_s_barrier()
; template <class Epi, class Sched>
; __device__ __forceinline__ void gemm_phase(LAS unsigned char* lds, const Gemm g, const Sched& S, const Epi& E) {
;     const int tid = threadIdx.x, wid = __builtin_amdgcn_readfirstlane(tid >> 6), lane = tid & 63, wr = wid >> 2, wc = wid & 3, fr = lane & 15, fq = lane >> 4;
;     unsigned voffA[2], voffB[2];
; #pragma unroll
;     for (int i = 0; i < 2; ++i) { int R, C; stage_rc(tid * 16 + i * 8192, R, C); const int Rb = Epi::PERM ? ((R & ~31) + perm32(R & 31)) : R;
;         voffA[i] = (unsigned)(R * g.lda + C) * 2u; voffB[i] = (unsigned)(Rb * g.ldb + C) * 2u; }
;     const size_t kstep = (size_t)(BK * 2);
;     const size_t hstepA = g.a_half ? g.a_half : (size_t)HALF * g.lda * 2, hstepB = g.b_half ? g.b_half : (size_t)HALF * g.ldb * 2;
;     const size_t tstepA = g.a_tile ? g.a_tile : (size_t)BM * g.lda * 2, tstepB = g.b_tile ? g.b_tile : (size_t)BM * g.ldb * 2;
;     const unsigned ldsw = (unsigned)wid * 1024u;
;     const int aoff = lds_byte(wr * 64 + fr, fq * 8), boff = lds_byte(wc * 32 + fr, fq * 8);
;     ...
;     Unit cur, nxt; int ui = 0;
;     if (!S.next(0, cur)) return;
;     f32x4 acc[2][2][4][2];
; #pragma unroll
;     for (int a = 0; a < 2; ++a)
; #pragma unroll
;         for (int b = 0; b < 2; ++b)
; #pragma unroll
;             for (int m = 0; m < 4; ++m)
; #pragma unroll
;                 for (int n = 0; n < 2; ++n) acc[a][b][m][n] = (f32x4){0.f, 0.f, 0.f, 0.f};
;     bf16x8 At[4][2], B0[2][2], B1[2][2];
;     const char* cA = (const char*)g.A + (size_t)cur.pm * tstepA + (size_t)cur.pn * g.a_pn_off + (size_t)cur.kt0 * kstep; const char* cB = (const char*)g.Bt + (size_t)cur.pn * tstepB + (size_t)cur.kt0 * kstep;
;     PG8_STAGE(PG8_SB(0, 0), cB, voffB); PG8_STAGE(PG8_SA(0, 0), cA, voffA); PG8_STAGE(PG8_SB(0, 1), cB + hstepB, voffB); PG8_STAGE(PG8_SA(0, 1), cA + hstepA, voffA);
;     if (wr == 1) PG8_BAR;
;     PG8_WAIT_V(4); PG8_BAR;
;     PG8_STAGE(PG8_SB(1, 0), cB + kstep, voffB); PG8_STAGE(PG8_SA(1, 0), cA + kstep, voffA); PG8_STAGE(PG8_SB(1, 1), cB + hstepB + kstep, voffB);
;     PG8_WAIT_V(6); PG8_BAR;
.LBB0_467:
	s_add_u32 s8, s84, 0x11d39000
	s_addc_u32 s9, s85, 0
	s_lshl_b32 s10, s10, 5
	s_and_b32 s17, s10, 0x60
	s_mov_b64 s[10:11], 0x80
	s_add_i32 m0, s13, 0x18000
	v_lshl_add_u64 v[6:7], v[6:7], 0, s[10:11]
	s_ashr_i32 s38, s96, 31
	s_lshl_b32 s16, s7, 13
	s_lshl_b32 s18, s17, 7
	s_waitcnt vmcnt(2)
	s_barrier
	global_load_lds_dwordx4 v[6:7], off
	v_lshl_add_u64 v[4:5], v[4:5], 0, s[10:11]
	s_add_i32 m0, s13, 0x1a000
	s_add_i32 s39, s13, 0x8000
	s_add_i32 s40, s13, 0xa000
	global_load_lds_dwordx4 v[4:5], off
	v_lshl_add_u64 v[2:3], v[2:3], 0, s[10:11]
	s_mov_b32 m0, s39
	s_add_u32 s14, s24, 0x80080
	global_load_lds_dwordx4 v[2:3], off
	v_lshl_add_u64 v[0:1], v[0:1], 0, s[10:11]
	s_mov_b32 m0, s40
	s_addc_u32 s15, s25, 0
	global_load_lds_dwordx4 v[0:1], off
	s_add_i32 m0, s13, 0x1c000
	v_lshl_add_u64 v[0:1], s[14:15], 0, v[130:131]
	global_load_lds_dwordx4 v[0:1], off
	v_lshl_add_u64 v[0:1], s[14:15], 0, v[134:135]
	s_add_i32 m0, s13, 0x1e000
	s_sext_i32_i16 s44, s6
	global_load_lds_dwordx4 v[0:1], off
	v_and_b32_e32 v0, 15, v160
	v_lshlrev_b32_e32 v1, 1, v11
	v_lshlrev_b32_e32 v2, 6, v160
	s_movk_i32 s6, 0x3c0
	v_and_or_b32 v2, v2, s6, v1
	v_and_b32_e32 v3, 32, v184
	v_lshl_or_b32 v144, s7, 6, v0
	v_lshl_or_b32 v0, v0, 6, v1
	v_lshlrev_b32_e32 v1, 9, v160
	v_bitop3_b32 v145, s18, v2, v3 bitop3:0xf6
	v_and_b32_e32 v1, 0x70000, v1
	v_lshlrev_b32_e32 v2, 12, v10
	v_or3_b32 v1, v8, v1, v2
	v_add_u32_e32 v136, v1, v9
	v_lshlrev_b32_e32 v1, 5, v12
	s_waitcnt vmcnt(6)
	v_and_b32_e32 v1, 0xf0000, v1
	v_bitop3_b32 v0, v0, s16, v3 bitop3:0xde
	v_or3_b32 v1, v8, v1, v2
	s_add_i32 s41, 0, 0x10000
	s_add_i32 s42, 0, 0x14000
	v_or_b32_e32 v146, s17, v11
	v_mov_b32_e32 v137, v131
	v_add_u32_e32 v138, v1, v9
	v_mov_b32_e32 v139, v131
	v_mov_b64_e32 v[140:141], 0x4ea
	v_mov_b64_e32 v[142:143], 0x4e9
	v_add_u32_e32 v147, s41, v145
	v_add_u32_e32 v148, 0, v0
	v_add_u32_e32 v149, s42, v145
	s_movk_i32 s43, 0x4a00
	s_barrier

; #define PG8_STAGE(bufoff, gbase, voff) do { _Pragma("unroll") for (int _i = 0; _i < 2; ++_i) \
;         __builtin_amdgcn_global_load_lds((const unsigned*)((const char*)(gbase) + (voff)[_i]), (LAS unsigned*)(lds + (bufoff) + ldsw + _i * 8192), 16, 0, 0); } while (0)
; #define PG8_LDA(dst, b, h) do { _Pragma("unroll") for (int m = 0; m < 4; ++m) _Pragma("unroll") for (int k = 0; k < 2; ++k) dst[m][k] = *(const LAS bf16x8*)(lds + PG8_SA(b, h) + aoff + m * 2048 + k * 1024); } while (0)
; #define PG8_LDB(dst, b, h) do { _Pragma("unroll") for (int n = 0; n < 2; ++n) _Pragma("unroll") for (int k = 0; k < 2; ++k) dst[n][k] = *(const LAS bf16x8*)(lds + PG8_SB(b, h) + boff + n * 2048 + k * 1024); } while (0)
; #define PG8_MMA(ai, bj, At, Bt) do { __builtin_amdgcn_s_setprio(1); _Pragma("unroll") for (int m = 0; m < 4; ++m) _Pragma("unroll") for (int n = 0; n < 2; ++n) _Pragma("unroll") for (int k = 0; k < 2; ++k) \
;         acc[ai][bj][m][n] = __builtin_amdgcn_mfma_f32_16x16x32_bf16(Bt[n][k], At[m][k], acc[ai][bj][m][n], 0, 0, 0); __builtin_amdgcn_s_setprio(0); } while (0)
; #define PG8_WAIT_V(n) asm volatile("s_waitcnt vmcnt(" #n ")" ::: "memory")
; #define PG8_WAIT_L(n) asm volatile("s_waitcnt lgkmcnt(" #n ")" ::: "memory")
; #define PG8_BAR __builtin_amdgcn_s_barrier()
; #define PG8_SCHED __builtin_amdgcn_sched_barrier(0)
; template <class Epi, class Sched>
; __device__ __forceinline__ void gemm_phase(LAS unsigned char* lds, const Gemm g, const Sched& S, const Epi& E) {
;     ...
;             PG8_LDB(B0, 0, 0); PG8_SCHED; PG8_LDA(At, 0, 0); PG8_STAGE(PG8_SA(1, 1), a1 + hstepA, voffA);
;             PG8_WAIT_L(8); PG8_BAR; PG8_WAIT_L(0); PG8_MMA(0, 0, At, B0); PG8_BAR; PG8_SCHED;
;             PG8_LDB(B1, 0, 1); PG8_STAGE(PG8_SB(0, 0), b2, voffB);
;             PG8_BAR; PG8_WAIT_L(0); if constexpr (!Epi::DIAG) PG8_MMA(0, 1, At, B1); PG8_BAR;
;             PG8_LDA(At, 0, 1); PG8_STAGE(PG8_SA(0, 0), a2, voffA);
;             PG8_BAR; PG8_WAIT_L(0); if constexpr (!Epi::DIAG) PG8_MMA(1, 0, At, B0); PG8_BAR; PG8_SCHED;
;             PG8_STAGE(PG8_SB(0, 1), b2 + hstepB, voffB);
;             PG8_WAIT_V(6); PG8_BAR; PG8_MMA(1, 1, At, B1); PG8_BAR;
.Lprio_475:
.LBB0_475:
	ds_read_b128 v[150:153], v147
	ds_read_b128 v[154:157], v147 offset:1024
	ds_read_b128 v[162:165], v147 offset:2048
	ds_read_b128 v[168:171], v147 offset:3072
	s_add_u32 s24, s22, 0xfff80080
	s_addc_u32 s25, s23, -1
	s_cmp_eq_u32 s49, 28
	s_cselect_b32 s27, s17, s25
	s_cselect_b32 s26, s45, s24
	s_cselect_b32 s25, s15, s48
	s_cselect_b32 s24, s46, s47
	v_lshl_add_u64 v[158:159], s[22:23], 0, v[136:137]
	s_add_i32 m0, s13, 0xc000
	ds_read_b128 v[172:175], v148
	ds_read_b128 v[176:179], v148 offset:1024
	ds_read_b128 v[180:183], v148 offset:2048
	ds_read_b128 v[186:189], v148 offset:3072
	ds_read_b128 v[190:193], v148 offset:4096
	ds_read_b128 v[194:197], v148 offset:5120
	ds_read_b128 v[198:201], v148 offset:6144
	ds_read_b128 v[202:205], v148 offset:7168
	global_load_lds_dwordx4 v[158:159], off
	v_lshl_add_u64 v[158:159], s[22:23], 0, v[138:139]
	s_add_i32 m0, s13, 0xe000
	s_nop 0
	global_load_lds_dwordx4 v[158:159], off
	ds_read_b128 v[206:209], v149
	ds_read_b128 v[210:213], v149 offset:1024
	ds_read_b128 v[214:217], v149 offset:2048
	ds_read_b128 v[218:221], v149 offset:3072
	s_waitcnt vmcnt(8)
	s_barrier
	s_waitcnt lgkmcnt(0)
	v_mfma_f32_16x16x32_bf16 v[124:127], v[150:153], v[172:175], v[124:127]
	v_mfma_f32_16x16x32_bf16 v[120:123], v[162:165], v[172:175], v[120:123]
	v_mfma_f32_16x16x32_bf16 v[116:119], v[150:153], v[180:183], v[116:119]
	v_mfma_f32_16x16x32_bf16 v[112:115], v[162:165], v[180:183], v[112:115]
	v_mfma_f32_16x16x32_bf16 v[100:103], v[150:153], v[190:193], v[100:103]
	v_mfma_f32_16x16x32_bf16 v[96:99], v[162:165], v[190:193], v[96:99]
	v_mfma_f32_16x16x32_bf16 v[84:87], v[150:153], v[198:201], v[84:87]
	v_mfma_f32_16x16x32_bf16 v[80:83], v[162:165], v[198:201], v[80:83]
	v_mfma_f32_16x16x32_bf16 v[124:127], v[154:157], v[176:179], v[124:127]
	v_mfma_f32_16x16x32_bf16 v[120:123], v[168:171], v[176:179], v[120:123]
	v_mfma_f32_16x16x32_bf16 v[116:119], v[154:157], v[186:189], v[116:119]
	v_mfma_f32_16x16x32_bf16 v[112:115], v[168:171], v[186:189], v[112:115]
	v_mfma_f32_16x16x32_bf16 v[100:103], v[154:157], v[194:197], v[100:103]
	v_mfma_f32_16x16x32_bf16 v[96:99], v[168:171], v[194:197], v[96:99]
	v_mfma_f32_16x16x32_bf16 v[84:87], v[154:157], v[202:205], v[84:87]
	v_mfma_f32_16x16x32_bf16 v[80:83], v[168:171], v[202:205], v[80:83]
	v_mfma_f32_16x16x32_bf16 v[108:111], v[206:209], v[172:175], v[108:111]
	v_mfma_f32_16x16x32_bf16 v[104:107], v[214:217], v[172:175], v[104:107]
	v_mfma_f32_16x16x32_bf16 v[92:95], v[206:209], v[180:183], v[92:95]
	v_mfma_f32_16x16x32_bf16 v[88:91], v[214:217], v[180:183], v[88:91]
	v_mfma_f32_16x16x32_bf16 v[76:79], v[206:209], v[190:193], v[76:79]
	v_mfma_f32_16x16x32_bf16 v[72:75], v[214:217], v[190:193], v[72:75]
	v_mfma_f32_16x16x32_bf16 v[68:71], v[206:209], v[198:201], v[68:71]
	v_mfma_f32_16x16x32_bf16 v[64:67], v[214:217], v[198:201], v[64:67]
	v_mfma_f32_16x16x32_bf16 v[108:111], v[210:213], v[176:179], v[108:111]
	v_mfma_f32_16x16x32_bf16 v[104:107], v[218:221], v[176:179], v[104:107]
	v_mfma_f32_16x16x32_bf16 v[92:95], v[210:213], v[186:189], v[92:95]
	v_mfma_f32_16x16x32_bf16 v[88:91], v[218:221], v[186:189], v[88:91]
	v_mfma_f32_16x16x32_bf16 v[76:79], v[210:213], v[194:197], v[76:79]
	v_mfma_f32_16x16x32_bf16 v[72:75], v[218:221], v[194:197], v[72:75]
	v_mfma_f32_16x16x32_bf16 v[68:71], v[210:213], v[202:205], v[68:71]
	v_mfma_f32_16x16x32_bf16 v[64:67], v[218:221], v[202:205], v[64:67]
	s_barrier
	ds_read_b128 v[172:175], v148 offset:16384
	ds_read_b128 v[176:179], v148 offset:17408
	ds_read_b128 v[180:183], v148 offset:18432
	ds_read_b128 v[186:189], v148 offset:19456
	ds_read_b128 v[190:193], v148 offset:20480
	ds_read_b128 v[194:197], v148 offset:21504
	ds_read_b128 v[198:201], v148 offset:22528
	ds_read_b128 v[202:205], v148 offset:23552
	s_add_i32 s50, s41, s30
	v_lshl_add_u64 v[158:159], s[24:25], 0, v[130:131]
	s_mov_b32 m0, s50
	s_nop 0
	global_load_lds_dwordx4 v[158:159], off
	v_lshl_add_u64 v[222:223], s[24:25], 0, v[134:135]
	s_add_i32 m0, s50, 0x2000
	s_nop 0
	global_load_lds_dwordx4 v[222:223], off
	s_mov_b32 m0, s13
	v_lshl_add_u64 v[224:225], s[26:27], 0, v[128:129]
	global_load_lds_dwordx4 v[224:225], off
	v_lshl_add_u64 v[226:227], s[26:27], 0, v[132:133]
	s_mov_b32 m0, s34
	s_nop 0
	global_load_lds_dwordx4 v[226:227], off
	s_add_u32 s50, s24, 0x80000
	s_addc_u32 s51, s25, 0
	s_add_i32 s52, s42, s30
	v_lshl_add_u64 v[230:231], s[50:51], 0, v[130:131]
	s_mov_b32 m0, s52
	s_nop 0
	global_load_lds_dwordx4 v[230:231], off
	v_lshl_add_u64 v[230:231], s[50:51], 0, v[134:135]
	s_add_i32 m0, s52, 0x2000
	s_nop 0
	global_load_lds_dwordx4 v[230:231], off
	s_waitcnt vmcnt(8)
	s_barrier
; #define PG8_STAGE(bufoff, gbase, voff) do { _Pragma("unroll") for (int _i = 0; _i < 2; ++_i) \
;         __builtin_amdgcn_global_load_lds((const unsigned*)((const char*)(gbase) + (voff)[_i]), (LAS unsigned*)(lds + (bufoff) + ldsw + _i * 8192), 16, 0, 0); } while (0)
; #define PG8_LDA(dst, b, h) do { _Pragma("unroll") for (int m = 0; m < 4; ++m) _Pragma("unroll") for (int k = 0; k < 2; ++k) dst[m][k] = *(const LAS bf16x8*)(lds + PG8_SA(b, h) + aoff + m * 2048 + k * 1024); } while (0)
; #define PG8_LDB(dst, b, h) do { _Pragma("unroll") for (int n = 0; n < 2; ++n) _Pragma("unroll") for (int k = 0; k < 2; ++k) dst[n][k] = *(const LAS bf16x8*)(lds + PG8_SB(b, h) + boff + n * 2048 + k * 1024); } while (0)
; #define PG8_MMA(ai, bj, At, Bt) do { __builtin_amdgcn_s_setprio(1); _Pragma("unroll") for (int m = 0; m < 4; ++m) _Pragma("unroll") for (int n = 0; n < 2; ++n) _Pragma("unroll") for (int k = 0; k < 2; ++k) \
;         acc[ai][bj][m][n] = __builtin_amdgcn_mfma_f32_16x16x32_bf16(Bt[n][k], At[m][k], acc[ai][bj][m][n], 0, 0, 0); __builtin_amdgcn_s_setprio(0); } while (0)
; #define PG8_WAIT_V(n) asm volatile("s_waitcnt vmcnt(" #n ")" ::: "memory")
; #define PG8_WAIT_L(n) asm volatile("s_waitcnt lgkmcnt(" #n ")" ::: "memory")
; #define PG8_BAR __builtin_amdgcn_s_barrier()
; #define PG8_SCHED __builtin_amdgcn_sched_barrier(0)
; template <class Epi, class Sched>
; __device__ __forceinline__ void gemm_phase(LAS unsigned char* lds, const Gemm g, const Sched& S, const Epi& E) {
;     ...
;             PG8_WAIT_V(6); PG8_BAR; PG8_MMA(1, 1, At, B1); PG8_BAR;
;             PG8_LDB(B0, 1, 0); PG8_SCHED; PG8_LDA(At, 1, 0); PG8_STAGE(PG8_SA(0, 1), a2 + hstepA, voffA);
;             PG8_WAIT_L(8); PG8_BAR; PG8_WAIT_L(0); PG8_MMA(0, 0, At, B0); PG8_BAR; PG8_SCHED;
;             PG8_LDB(B1, 1, 1); PG8_STAGE(PG8_SB(1, 0), b3, voffB);
;             PG8_BAR; PG8_WAIT_L(0); if constexpr (!Epi::DIAG) PG8_MMA(0, 1, At, B1); PG8_BAR;
;             PG8_LDA(At, 1, 1); PG8_STAGE(PG8_SA(1, 0), a3, voffA);
;             PG8_BAR; PG8_WAIT_L(0); if constexpr (!Epi::DIAG) PG8_MMA(1, 0, At, B0); PG8_BAR; PG8_SCHED;
	s_waitcnt lgkmcnt(0)
	v_mfma_f32_16x16x32_bf16 v[60:63], v[150:153], v[172:175], v[60:63]
	v_mfma_f32_16x16x32_bf16 v[56:59], v[162:165], v[172:175], v[56:59]
	v_mfma_f32_16x16x32_bf16 v[52:55], v[150:153], v[180:183], v[52:55]
	v_mfma_f32_16x16x32_bf16 v[48:51], v[162:165], v[180:183], v[48:51]
	v_mfma_f32_16x16x32_bf16 v[36:39], v[150:153], v[190:193], v[36:39]
	v_mfma_f32_16x16x32_bf16 v[32:35], v[162:165], v[190:193], v[32:35]
	v_mfma_f32_16x16x32_bf16 v[20:23], v[150:153], v[198:201], v[20:23]
	v_mfma_f32_16x16x32_bf16 v[16:19], v[162:165], v[198:201], v[16:19]
	v_mfma_f32_16x16x32_bf16 v[60:63], v[154:157], v[176:179], v[60:63]
	v_mfma_f32_16x16x32_bf16 v[56:59], v[168:171], v[176:179], v[56:59]
	v_mfma_f32_16x16x32_bf16 v[52:55], v[154:157], v[186:189], v[52:55]
	v_mfma_f32_16x16x32_bf16 v[48:51], v[168:171], v[186:189], v[48:51]
	v_mfma_f32_16x16x32_bf16 v[36:39], v[154:157], v[194:197], v[36:39]
	v_mfma_f32_16x16x32_bf16 v[32:35], v[168:171], v[194:197], v[32:35]
	v_mfma_f32_16x16x32_bf16 v[20:23], v[154:157], v[202:205], v[20:23]
	v_mfma_f32_16x16x32_bf16 v[16:19], v[168:171], v[202:205], v[16:19]
	v_mfma_f32_16x16x32_bf16 v[44:47], v[206:209], v[172:175], v[44:47]
	v_mfma_f32_16x16x32_bf16 v[40:43], v[214:217], v[172:175], v[40:43]
	v_mfma_f32_16x16x32_bf16 v[28:31], v[206:209], v[180:183], v[28:31]
	v_mfma_f32_16x16x32_bf16 v[24:27], v[214:217], v[180:183], v[24:27]
	v_mfma_f32_16x16x32_bf16 v[12:15], v[206:209], v[190:193], v[12:15]
	v_mfma_f32_16x16x32_bf16 v[8:11], v[214:217], v[190:193], v[8:11]
	v_mfma_f32_16x16x32_bf16 v[4:7], v[206:209], v[198:201], v[4:7]
	v_mfma_f32_16x16x32_bf16 v[0:3], v[214:217], v[198:201], v[0:3]
	v_mfma_f32_16x16x32_bf16 v[44:47], v[210:213], v[176:179], v[44:47]
	v_mfma_f32_16x16x32_bf16 v[40:43], v[218:221], v[176:179], v[40:43]
	v_mfma_f32_16x16x32_bf16 v[28:31], v[210:213], v[186:189], v[28:31]
	v_mfma_f32_16x16x32_bf16 v[24:27], v[218:221], v[186:189], v[24:27]
	v_mfma_f32_16x16x32_bf16 v[12:15], v[210:213], v[194:197], v[12:15]
	v_mfma_f32_16x16x32_bf16 v[8:11], v[218:221], v[194:197], v[8:11]
	v_mfma_f32_16x16x32_bf16 v[4:7], v[210:213], v[202:205], v[4:7]
	v_mfma_f32_16x16x32_bf16 v[0:3], v[218:221], v[202:205], v[0:3]
	s_barrier
	s_add_i32 s50, 0, 0x18000
	v_add_u32_e32 v161, s50, v145
	ds_read_b128 v[150:153], v161
	ds_read_b128 v[154:157], v161 offset:1024
	ds_read_b128 v[162:165], v161 offset:2048
	ds_read_b128 v[168:171], v161 offset:3072
	ds_read_b128 v[172:175], v148 offset:32768
	ds_read_b128 v[176:179], v148 offset:33792
	ds_read_b128 v[180:183], v148 offset:34816
	ds_read_b128 v[186:189], v148 offset:35840
	ds_read_b128 v[190:193], v148 offset:36864
	ds_read_b128 v[194:197], v148 offset:37888
	ds_read_b128 v[198:201], v148 offset:38912
	ds_read_b128 v[202:205], v148 offset:39936
	s_add_u32 s26, s26, 0x80000
	s_addc_u32 s27, s27, 0
	s_mov_b32 m0, s35
	v_lshl_add_u64 v[230:231], s[26:27], 0, v[128:129]
	global_load_lds_dwordx4 v[230:231], off
	v_lshl_add_u64 v[230:231], s[26:27], 0, v[132:133]
	s_mov_b32 m0, s36
	s_nop 0
	global_load_lds_dwordx4 v[230:231], off
	s_add_i32 s26, 0, 0x1c000
	s_add_i32 s27, s50, s30
	v_add_u32_e32 v161, s26, v145
	ds_read_b128 v[206:209], v161
	ds_read_b128 v[210:213], v161 offset:1024
	ds_read_b128 v[214:217], v161 offset:2048
	ds_read_b128 v[218:221], v161 offset:3072
	s_waitcnt vmcnt(8)
	s_barrier
	s_waitcnt lgkmcnt(0)
	v_mfma_f32_16x16x32_bf16 v[124:127], v[150:153], v[172:175], v[124:127]
	v_mfma_f32_16x16x32_bf16 v[120:123], v[162:165], v[172:175], v[120:123]
	v_mfma_f32_16x16x32_bf16 v[116:119], v[150:153], v[180:183], v[116:119]
	v_mfma_f32_16x16x32_bf16 v[112:115], v[162:165], v[180:183], v[112:115]
	v_mfma_f32_16x16x32_bf16 v[100:103], v[150:153], v[190:193], v[100:103]
	v_mfma_f32_16x16x32_bf16 v[96:99], v[162:165], v[190:193], v[96:99]
	v_mfma_f32_16x16x32_bf16 v[84:87], v[150:153], v[198:201], v[84:87]
	v_mfma_f32_16x16x32_bf16 v[80:83], v[162:165], v[198:201], v[80:83]
	v_mfma_f32_16x16x32_bf16 v[124:127], v[154:157], v[176:179], v[124:127]
	v_mfma_f32_16x16x32_bf16 v[120:123], v[168:171], v[176:179], v[120:123]
	v_mfma_f32_16x16x32_bf16 v[116:119], v[154:157], v[186:189], v[116:119]
	v_mfma_f32_16x16x32_bf16 v[112:115], v[168:171], v[186:189], v[112:115]
	v_mfma_f32_16x16x32_bf16 v[100:103], v[154:157], v[194:197], v[100:103]
	v_mfma_f32_16x16x32_bf16 v[96:99], v[168:171], v[194:197], v[96:99]
	v_mfma_f32_16x16x32_bf16 v[84:87], v[154:157], v[202:205], v[84:87]
	v_mfma_f32_16x16x32_bf16 v[80:83], v[168:171], v[202:205], v[80:83]
	v_mfma_f32_16x16x32_bf16 v[108:111], v[206:209], v[172:175], v[108:111]
	v_mfma_f32_16x16x32_bf16 v[104:107], v[214:217], v[172:175], v[104:107]
	v_mfma_f32_16x16x32_bf16 v[92:95], v[206:209], v[180:183], v[92:95]
	v_mfma_f32_16x16x32_bf16 v[88:91], v[214:217], v[180:183], v[88:91]
	v_mfma_f32_16x16x32_bf16 v[76:79], v[206:209], v[190:193], v[76:79]
	v_mfma_f32_16x16x32_bf16 v[72:75], v[214:217], v[190:193], v[72:75]
	v_mfma_f32_16x16x32_bf16 v[68:71], v[206:209], v[198:201], v[68:71]
	v_mfma_f32_16x16x32_bf16 v[64:67], v[214:217], v[198:201], v[64:67]
	v_mfma_f32_16x16x32_bf16 v[108:111], v[210:213], v[176:179], v[108:111]
	v_mfma_f32_16x16x32_bf16 v[104:107], v[218:221], v[176:179], v[104:107]
	v_mfma_f32_16x16x32_bf16 v[92:95], v[210:213], v[186:189], v[92:95]
	v_mfma_f32_16x16x32_bf16 v[88:91], v[218:221], v[186:189], v[88:91]
	v_mfma_f32_16x16x32_bf16 v[76:79], v[210:213], v[194:197], v[76:79]
	v_mfma_f32_16x16x32_bf16 v[72:75], v[218:221], v[194:197], v[72:75]
	v_mfma_f32_16x16x32_bf16 v[68:71], v[210:213], v[202:205], v[68:71]
	v_mfma_f32_16x16x32_bf16 v[64:67], v[218:221], v[202:205], v[64:67]
	s_barrier
; #define PG8_STAGE(bufoff, gbase, voff) do { _Pragma("unroll") for (int _i = 0; _i < 2; ++_i) \
;         __builtin_amdgcn_global_load_lds((const unsigned*)((const char*)(gbase) + (voff)[_i]), (LAS unsigned*)(lds + (bufoff) + ldsw + _i * 8192), 16, 0, 0); } while (0)
; #define PG8_LDA(dst, b, h) do { _Pragma("unroll") for (int m = 0; m < 4; ++m) _Pragma("unroll") for (int k = 0; k < 2; ++k) dst[m][k] = *(const LAS bf16x8*)(lds + PG8_SA(b, h) + aoff + m * 2048 + k * 1024); } while (0)
; #define PG8_MMA(ai, bj, At, Bt) do { __builtin_amdgcn_s_setprio(1); _Pragma("unroll") for (int m = 0; m < 4; ++m) _Pragma("unroll") for (int n = 0; n < 2; ++n) _Pragma("unroll") for (int k = 0; k < 2; ++k) \
;         acc[ai][bj][m][n] = __builtin_amdgcn_mfma_f32_16x16x32_bf16(Bt[n][k], At[m][k], acc[ai][bj][m][n], 0, 0, 0); __builtin_amdgcn_s_setprio(0); } while (0)
; #define PG8_WAIT_V(n) asm volatile("s_waitcnt vmcnt(" #n ")" ::: "memory")
; #define PG8_WAIT_L(n) asm volatile("s_waitcnt lgkmcnt(" #n ")" ::: "memory")
; #define PG8_BAR __builtin_amdgcn_s_barrier()
; #define PG8_SCHED __builtin_amdgcn_sched_barrier(0)
; template <class Epi, class Sched>
; __device__ __forceinline__ void gemm_phase(LAS unsigned char* lds, const Gemm g, const Sched& S, const Epi& E) {
;     ...
;             PG8_LDA(At, 1, 1); PG8_STAGE(PG8_SA(1, 0), a3, voffA);
;             PG8_BAR; PG8_WAIT_L(0); if constexpr (!Epi::DIAG) PG8_MMA(1, 0, At, B0); PG8_BAR; PG8_SCHED;
;             PG8_STAGE(PG8_SB(1, 1), b3 + hstepB, voffB);
;             PG8_WAIT_V(6); PG8_BAR; PG8_MMA(1, 1, At, B1); PG8_BAR;
	ds_read_b128 v[172:175], v148 offset:49152
	ds_read_b128 v[176:179], v148 offset:50176
	ds_read_b128 v[180:183], v148 offset:51200
	ds_read_b128 v[186:189], v148 offset:52224
	ds_read_b128 v[190:193], v148 offset:53248
	ds_read_b128 v[194:197], v148 offset:54272
	ds_read_b128 v[198:201], v148 offset:55296
	ds_read_b128 v[202:205], v148 offset:56320
	v_lshl_add_u64 v[158:159], v[158:159], 0, s[10:11]
	s_mov_b32 m0, s27
	s_nop 0
	global_load_lds_dwordx4 v[158:159], off
	v_lshl_add_u64 v[158:159], v[222:223], 0, s[10:11]
	s_add_i32 m0, s27, 0x2000
	s_nop 0
	global_load_lds_dwordx4 v[158:159], off
	s_mov_b32 m0, s39
	v_lshl_add_u64 v[158:159], v[224:225], 0, s[10:11]
	global_load_lds_dwordx4 v[158:159], off
	v_lshl_add_u64 v[158:159], v[226:227], 0, s[10:11]
	s_mov_b32 m0, s40
	s_nop 0
	global_load_lds_dwordx4 v[158:159], off
	s_add_u32 s24, s24, 0x80080
	s_addc_u32 s25, s25, 0
	s_add_i32 s26, s26, s30
	v_lshl_add_u64 v[230:231], s[24:25], 0, v[130:131]
	s_mov_b32 m0, s26
	s_nop 0
	global_load_lds_dwordx4 v[230:231], off
	v_lshl_add_u64 v[230:231], s[24:25], 0, v[134:135]
	s_add_i32 m0, s26, 0x2000
	s_nop 0
	global_load_lds_dwordx4 v[230:231], off
	s_waitcnt vmcnt(8)
	s_barrier
	s_waitcnt lgkmcnt(0)
	v_mfma_f32_16x16x32_bf16 v[60:63], v[150:153], v[172:175], v[60:63]
	v_mfma_f32_16x16x32_bf16 v[56:59], v[162:165], v[172:175], v[56:59]
	v_mfma_f32_16x16x32_bf16 v[52:55], v[150:153], v[180:183], v[52:55]
	v_mfma_f32_16x16x32_bf16 v[48:51], v[162:165], v[180:183], v[48:51]
	v_mfma_f32_16x16x32_bf16 v[36:39], v[150:153], v[190:193], v[36:39]
	v_mfma_f32_16x16x32_bf16 v[32:35], v[162:165], v[190:193], v[32:35]
	v_mfma_f32_16x16x32_bf16 v[20:23], v[150:153], v[198:201], v[20:23]
	v_mfma_f32_16x16x32_bf16 v[16:19], v[162:165], v[198:201], v[16:19]
	v_mfma_f32_16x16x32_bf16 v[60:63], v[154:157], v[176:179], v[60:63]
	v_mfma_f32_16x16x32_bf16 v[56:59], v[168:171], v[176:179], v[56:59]
	v_mfma_f32_16x16x32_bf16 v[52:55], v[154:157], v[186:189], v[52:55]
	v_mfma_f32_16x16x32_bf16 v[48:51], v[168:171], v[186:189], v[48:51]
	v_mfma_f32_16x16x32_bf16 v[36:39], v[154:157], v[194:197], v[36:39]
	v_mfma_f32_16x16x32_bf16 v[32:35], v[168:171], v[194:197], v[32:35]
	v_mfma_f32_16x16x32_bf16 v[20:23], v[154:157], v[202:205], v[20:23]
	v_mfma_f32_16x16x32_bf16 v[16:19], v[168:171], v[202:205], v[16:19]
	v_mfma_f32_16x16x32_bf16 v[44:47], v[206:209], v[172:175], v[44:47]
	v_mfma_f32_16x16x32_bf16 v[40:43], v[214:217], v[172:175], v[40:43]
	v_mfma_f32_16x16x32_bf16 v[28:31], v[206:209], v[180:183], v[28:31]
	v_mfma_f32_16x16x32_bf16 v[24:27], v[214:217], v[180:183], v[24:27]
	v_mfma_f32_16x16x32_bf16 v[12:15], v[206:209], v[190:193], v[12:15]
	v_mfma_f32_16x16x32_bf16 v[8:11], v[214:217], v[190:193], v[8:11]
	v_mfma_f32_16x16x32_bf16 v[4:7], v[206:209], v[198:201], v[4:7]
	v_mfma_f32_16x16x32_bf16 v[0:3], v[214:217], v[198:201], v[0:3]
	v_mfma_f32_16x16x32_bf16 v[44:47], v[210:213], v[176:179], v[44:47]
	v_mfma_f32_16x16x32_bf16 v[40:43], v[218:221], v[176:179], v[40:43]
	v_mfma_f32_16x16x32_bf16 v[28:31], v[210:213], v[186:189], v[28:31]
	v_mfma_f32_16x16x32_bf16 v[24:27], v[218:221], v[186:189], v[24:27]
	v_mfma_f32_16x16x32_bf16 v[12:15], v[210:213], v[194:197], v[12:15]
	v_mfma_f32_16x16x32_bf16 v[8:11], v[218:221], v[194:197], v[8:11]
	v_mfma_f32_16x16x32_bf16 v[4:7], v[210:213], v[202:205], v[4:7]
	v_mfma_f32_16x16x32_bf16 v[0:3], v[218:221], v[202:205], v[0:3]
	s_add_i32 s49, s49, 2
	s_add_u32 s22, s22, 0x100
	s_addc_u32 s23, s23, 0
	s_add_u32 s47, s47, 0x100
	s_addc_u32 s48, s48, 0
	s_cmp_gt_u32 s49, 29
	s_barrier
	s_cbranch_scc0 .LBB0_475
; __device__ __forceinline__ unsigned pk2(float lo, float hi) { const f32x2 v = {lo, hi}; const bf16x2_hw b = __builtin_convertvector(v, bf16x2_hw); return __builtin_bit_cast(unsigned, b); }
;     __device__ __forceinline__ void operator()(const Acc& acc, const Unit& u, int wr, int wc, int fr, int fq) const { if (u.piece == 0) e1(acc, u, wr, wc, fr, fq); else e2(acc, u, wr, wc, fr, fq); }
;     __device__ __forceinline__ void operator()(const Acc& acc, const Unit& u, int wr, int wc, int fr, int fq) const {
;         const int row0 = u.pm * BM + wr * 64 + fr, col0 = u.pn * BM + wc * 32 + 8 * fq;
; #pragma unroll
;         for (int ai = 0; ai < 2; ++ai)
; #pragma unroll
;             for (int m = 0; m < 4; ++m) { bf16_t* rowp = O + (size_t)(row0 + ai * HALF + m * 16) * ldc + col_off + col0;
; #pragma unroll
;                 for (int bj = 0; bj < 2; ++bj) { f32x4 v0 = acc[ai][bj][m][0], v1 = acc[ai][bj][m][1];
;                     if (scale) { v0 *= *(const f32x4*)(scale + col0 + bj * HALF); v1 *= *(const f32x4*)(scale + col0 + bj * HALF + 4); }
;                     u32x4 w; w.x = pk2(v0[0], v0[1]); w.y = pk2(v0[2], v0[3]); w.z = pk2(v1[0], v1[1]); w.w = pk2(v1[2], v1[3]);
;                     *(u32x4*)(rowp + bj * HALF) = w; }
;                 if (scale) asm volatile("" ::: "memory"); }
;     }
	s_setprio 0
	v_lshl_add_u32 v156, s12, 8, v144
	v_lshl_or_b32 v150, s44, 8, v146
	v_ashrrev_i32_e32 v151, 31, v150
	v_mov_b64_e32 v[152:153], s[8:9]
	v_cvt_pk_bf16_f32 v68, v68, v69
	v_cvt_pk_bf16_f32 v69, v70, v71
	v_cvt_pk_bf16_f32 v70, v64, v65
	v_add_u32_e32 v64, 0x80, v156
	v_mad_i64_i32 v[154:155], s[22:23], v156, s43, v[152:153]
	v_lshlrev_b64 v[150:151], 1, v[150:151]
	v_cvt_pk_bf16_f32 v108, v108, v109
	v_cvt_pk_bf16_f32 v109, v110, v111
	v_cvt_pk_bf16_f32 v110, v104, v105
	v_or_b32_e32 v104, 16, v156
	v_mad_i64_i32 v[64:65], s[22:23], v64, s43, v[152:153]
	v_cvt_pk_bf16_f32 v44, v44, v45
	v_cvt_pk_bf16_f32 v45, v46, v47
	v_cvt_pk_bf16_f32 v46, v40, v41
	v_add_u32_e32 v40, 0x90, v156
	v_lshl_add_u64 v[154:155], v[154:155], 0, v[150:151]
	v_cvt_pk_bf16_f32 v111, v106, v107
	v_mad_i64_i32 v[104:105], s[22:23], v104, s43, v[152:153]
	v_cvt_pk_bf16_f32 v92, v92, v93
	v_cvt_pk_bf16_f32 v93, v94, v95
	v_cvt_pk_bf16_f32 v94, v88, v89
	v_or_b32_e32 v88, 32, v156
	v_lshl_add_u64 v[64:65], v[64:65], 0, v[150:151]
	v_cvt_pk_bf16_f32 v47, v42, v43
	v_mad_i64_i32 v[40:41], s[22:23], v40, s43, v[152:153]
	v_cvt_pk_bf16_f32 v28, v28, v29
	v_cvt_pk_bf16_f32 v29, v30, v31
	v_cvt_pk_bf16_f32 v30, v24, v25
	v_add_u32_e32 v24, 0xa0, v156
	global_store_dwordx4 v[154:155], v[108:111], off offset:256
	v_cvt_pk_bf16_f32 v95, v90, v91
	v_mad_i64_i32 v[88:89], s[22:23], v88, s43, v[152:153]
	v_lshl_add_u64 v[108:109], v[104:105], 0, v[150:151]
	v_cvt_pk_bf16_f32 v76, v76, v77
	v_cvt_pk_bf16_f32 v77, v78, v79
	v_cvt_pk_bf16_f32 v78, v72, v73
	v_or_b32_e32 v72, 48, v156
	global_store_dwordx4 v[64:65], v[44:47], off offset:256
	v_cvt_pk_bf16_f32 v31, v26, v27
	v_mad_i64_i32 v[24:25], s[22:23], v24, s43, v[152:153]
	v_lshl_add_u64 v[44:45], v[40:41], 0, v[150:151]
	v_cvt_pk_bf16_f32 v12, v12, v13
	v_cvt_pk_bf16_f32 v13, v14, v15
	v_cvt_pk_bf16_f32 v14, v8, v9
	v_add_u32_e32 v8, 0xb0, v156
	global_store_dwordx4 v[108:109], v[92:95], off offset:256
	v_cvt_pk_bf16_f32 v79, v74, v75
	v_mad_i64_i32 v[72:73], s[22:23], v72, s43, v[152:153]
	v_lshl_add_u64 v[92:93], v[88:89], 0, v[150:151]
	global_store_dwordx4 v[44:45], v[28:31], off offset:256
	v_cvt_pk_bf16_f32 v15, v10, v11
	v_mad_i64_i32 v[8:9], s[22:23], v8, s43, v[152:153]
	v_lshl_add_u64 v[28:29], v[24:25], 0, v[150:151]
	v_cvt_pk_bf16_f32 v124, v124, v125
	v_cvt_pk_bf16_f32 v125, v126, v127
	v_cvt_pk_bf16_f32 v126, v120, v121
	v_cvt_pk_bf16_f32 v127, v122, v123
	v_cvt_pk_bf16_f32 v104, v116, v117
	v_cvt_pk_bf16_f32 v105, v118, v119
	v_cvt_pk_bf16_f32 v106, v112, v113
	v_cvt_pk_bf16_f32 v107, v114, v115
	v_cvt_pk_bf16_f32 v88, v100, v101
	v_cvt_pk_bf16_f32 v89, v102, v103
	v_cvt_pk_bf16_f32 v90, v96, v97
	v_cvt_pk_bf16_f32 v91, v98, v99
	global_store_dwordx4 v[92:93], v[76:79], off offset:256
	v_cvt_pk_bf16_f32 v74, v80, v81
	v_cvt_pk_bf16_f32 v75, v82, v83
	v_lshl_add_u64 v[76:77], v[72:73], 0, v[150:151]
	v_cvt_pk_bf16_f32 v72, v84, v85
	v_cvt_pk_bf16_f32 v73, v86, v87
	v_cvt_pk_bf16_f32 v71, v66, v67
	v_cvt_pk_bf16_f32 v60, v60, v61
	v_cvt_pk_bf16_f32 v61, v62, v63
	v_cvt_pk_bf16_f32 v62, v56, v57
	v_cvt_pk_bf16_f32 v63, v58, v59
	v_cvt_pk_bf16_f32 v40, v52, v53
	v_cvt_pk_bf16_f32 v41, v54, v55
	v_cvt_pk_bf16_f32 v42, v48, v49
	v_cvt_pk_bf16_f32 v43, v50, v51
	v_cvt_pk_bf16_f32 v24, v36, v37
	v_cvt_pk_bf16_f32 v25, v38, v39
	v_cvt_pk_bf16_f32 v26, v32, v33
	v_cvt_pk_bf16_f32 v27, v34, v35
	global_store_dwordx4 v[28:29], v[12:15], off offset:256
	v_cvt_pk_bf16_f32 v10, v16, v17
	v_cvt_pk_bf16_f32 v11, v18, v19
	v_lshl_add_u64 v[12:13], v[8:9], 0, v[150:151]
	v_cvt_pk_bf16_f32 v8, v20, v21
	v_cvt_pk_bf16_f32 v9, v22, v23
	v_cvt_pk_bf16_f32 v4, v4, v5
	v_cvt_pk_bf16_f32 v5, v6, v7
	v_cvt_pk_bf16_f32 v6, v0, v1
	v_cvt_pk_bf16_f32 v7, v2, v3
	s_and_b64 vcc, exec, s[6:7]
	s_mov_b32 s44, s14
	s_mov_b32 s12, s16
	s_mov_b64 s[24:25], s[20:21]
	s_mov_b64 s[22:23], s[18:19]
	global_store_dwordx4 v[154:155], v[124:127], off
	global_store_dwordx4 v[108:109], v[104:107], off
	global_store_dwordx4 v[92:93], v[88:91], off
	global_store_dwordx4 v[76:77], v[72:75], off
	global_store_dwordx4 v[76:77], v[68:71], off offset:256
	global_store_dwordx4 v[64:65], v[60:63], off
	global_store_dwordx4 v[44:45], v[40:43], off
	global_store_dwordx4 v[28:29], v[24:27], off
	global_store_dwordx4 v[12:13], v[8:11], off
	global_store_dwordx4 v[12:13], v[4:7], off offset:256
	s_cbranch_vccz .LBB0_468
	s_waitcnt vmcnt(0)
	s_cmpk_gt_u32 s3, 0xff
	s_cbranch_scc1 .LBB0_479
	s_barrier

; #define PG8_STAGE(bufoff, gbase, voff) do { _Pragma("unroll") for (int _i = 0; _i < 2; ++_i) \
;         __builtin_amdgcn_global_load_lds((const unsigned*)((const char*)(gbase) + (voff)[_i]), (LAS unsigned*)(lds + (bufoff) + ldsw + _i * 8192), 16, 0, 0); } while (0)
; #define PG8_LDA(dst, b, h) do { _Pragma("unroll") for (int m = 0; m < 4; ++m) _Pragma("unroll") for (int k = 0; k < 2; ++k) dst[m][k] = *(const LAS bf16x8*)(lds + PG8_SA(b, h) + aoff + m * 2048 + k * 1024); } while (0)
; #define PG8_LDB(dst, b, h) do { _Pragma("unroll") for (int n = 0; n < 2; ++n) _Pragma("unroll") for (int k = 0; k < 2; ++k) dst[n][k] = *(const LAS bf16x8*)(lds + PG8_SB(b, h) + boff + n * 2048 + k * 1024); } while (0)
; #define PG8_MMA(ai, bj, At, Bt) do { __builtin_amdgcn_s_setprio(1); _Pragma("unroll") for (int m = 0; m < 4; ++m) _Pragma("unroll") for (int n = 0; n < 2; ++n) _Pragma("unroll") for (int k = 0; k < 2; ++k) \
;         acc[ai][bj][m][n] = __builtin_amdgcn_mfma_f32_16x16x32_bf16(Bt[n][k], At[m][k], acc[ai][bj][m][n], 0, 0, 0); __builtin_amdgcn_s_setprio(0); } while (0)
; #define PG8_WAIT_V(n) asm volatile("s_waitcnt vmcnt(" #n ")" ::: "memory")
; #define PG8_WAIT_L(n) asm volatile("s_waitcnt lgkmcnt(" #n ")" ::: "memory")
; #define PG8_BAR __builtin_amdgcn_s_barrier()
; #define PG8_SCHED __builtin_amdgcn_sched_barrier(0)
; template <class Epi, class Sched>
; __device__ __forceinline__ void gemm_phase(LAS unsigned char* lds, const Gemm g, const Sched& S, const Epi& E) {
;     ...
;             PG8_LDB(B0, 0, 0); PG8_SCHED; PG8_LDA(At, 0, 0); PG8_STAGE(PG8_SA(1, 1), a1 + hstepA, voffA);
;             PG8_WAIT_L(8); PG8_BAR; PG8_WAIT_L(0); PG8_MMA(0, 0, At, B0); PG8_BAR; PG8_SCHED;
;             PG8_LDB(B1, 0, 1); PG8_STAGE(PG8_SB(0, 0), b2, voffB);
;             PG8_BAR; PG8_WAIT_L(0); if constexpr (!Epi::DIAG) PG8_MMA(0, 1, At, B1); PG8_BAR;
;             PG8_LDA(At, 0, 1); PG8_STAGE(PG8_SA(0, 0), a2, voffA);
;             PG8_BAR; PG8_WAIT_L(0); if constexpr (!Epi::DIAG) PG8_MMA(1, 0, At, B0); PG8_BAR; PG8_SCHED;
;             PG8_STAGE(PG8_SB(0, 1), b2 + hstepB, voffB);
;             PG8_WAIT_V(6); PG8_BAR; PG8_MMA(1, 1, At, B1); PG8_BAR;
.Lprio_1843:
.LBB0_1843:
	ds_read_b128 v[150:153], v147
	ds_read_b128 v[154:157], v147 offset:1024
	ds_read_b128 v[162:165], v147 offset:2048
	ds_read_b128 v[166:169], v147 offset:3072
	s_add_u32 s24, s22, 0xfff80080
	s_addc_u32 s25, s23, -1
	s_cmp_eq_u32 s52, 28
	s_cselect_b32 s27, s15, s25
	s_cselect_b32 s26, s48, s24
	s_cselect_b32 s25, s13, s51
	s_cselect_b32 s24, s49, s50
	v_lshl_add_u64 v[158:159], s[22:23], 0, v[136:137]
	s_add_i32 m0, s21, 0xc000
	ds_read_b128 v[170:173], v148
	ds_read_b128 v[174:177], v148 offset:1024
	ds_read_b128 v[178:181], v148 offset:2048
	ds_read_b128 v[186:189], v148 offset:3072
	ds_read_b128 v[190:193], v148 offset:4096
	ds_read_b128 v[194:197], v148 offset:5120
	ds_read_b128 v[198:201], v148 offset:6144
	ds_read_b128 v[202:205], v148 offset:7168
	global_load_lds_dwordx4 v[158:159], off
	v_lshl_add_u64 v[158:159], s[22:23], 0, v[138:139]
	s_add_i32 m0, s21, 0xe000
	s_nop 0
	global_load_lds_dwordx4 v[158:159], off
	ds_read_b128 v[206:209], v149
	ds_read_b128 v[210:213], v149 offset:1024
	ds_read_b128 v[214:217], v149 offset:2048
	ds_read_b128 v[218:221], v149 offset:3072
	s_waitcnt vmcnt(8)
	s_barrier
	s_waitcnt lgkmcnt(0)
	v_mfma_f32_16x16x32_bf16 v[124:127], v[150:153], v[170:173], v[124:127]
	v_mfma_f32_16x16x32_bf16 v[116:119], v[162:165], v[170:173], v[116:119]
	v_mfma_f32_16x16x32_bf16 v[108:111], v[150:153], v[178:181], v[108:111]
	v_mfma_f32_16x16x32_bf16 v[100:103], v[162:165], v[178:181], v[100:103]
	v_mfma_f32_16x16x32_bf16 v[92:95], v[150:153], v[190:193], v[92:95]
	v_mfma_f32_16x16x32_bf16 v[84:87], v[162:165], v[190:193], v[84:87]
	v_mfma_f32_16x16x32_bf16 v[76:79], v[150:153], v[198:201], v[76:79]
	v_mfma_f32_16x16x32_bf16 v[68:71], v[162:165], v[198:201], v[68:71]
	v_mfma_f32_16x16x32_bf16 v[124:127], v[154:157], v[174:177], v[124:127]
	v_mfma_f32_16x16x32_bf16 v[116:119], v[166:169], v[174:177], v[116:119]
	v_mfma_f32_16x16x32_bf16 v[108:111], v[154:157], v[186:189], v[108:111]
	v_mfma_f32_16x16x32_bf16 v[100:103], v[166:169], v[186:189], v[100:103]
	v_mfma_f32_16x16x32_bf16 v[92:95], v[154:157], v[194:197], v[92:95]
	v_mfma_f32_16x16x32_bf16 v[84:87], v[166:169], v[194:197], v[84:87]
	v_mfma_f32_16x16x32_bf16 v[76:79], v[154:157], v[202:205], v[76:79]
	v_mfma_f32_16x16x32_bf16 v[68:71], v[166:169], v[202:205], v[68:71]
	v_mfma_f32_16x16x32_bf16 v[120:123], v[206:209], v[170:173], v[120:123]
	v_mfma_f32_16x16x32_bf16 v[112:115], v[214:217], v[170:173], v[112:115]
	v_mfma_f32_16x16x32_bf16 v[104:107], v[206:209], v[178:181], v[104:107]
	v_mfma_f32_16x16x32_bf16 v[96:99], v[214:217], v[178:181], v[96:99]
	v_mfma_f32_16x16x32_bf16 v[88:91], v[206:209], v[190:193], v[88:91]
	v_mfma_f32_16x16x32_bf16 v[80:83], v[214:217], v[190:193], v[80:83]
	v_mfma_f32_16x16x32_bf16 v[72:75], v[206:209], v[198:201], v[72:75]
	v_mfma_f32_16x16x32_bf16 v[64:67], v[214:217], v[198:201], v[64:67]
	v_mfma_f32_16x16x32_bf16 v[120:123], v[210:213], v[174:177], v[120:123]
	v_mfma_f32_16x16x32_bf16 v[112:115], v[218:221], v[174:177], v[112:115]
	v_mfma_f32_16x16x32_bf16 v[104:107], v[210:213], v[186:189], v[104:107]
	v_mfma_f32_16x16x32_bf16 v[96:99], v[218:221], v[186:189], v[96:99]
	v_mfma_f32_16x16x32_bf16 v[88:91], v[210:213], v[194:197], v[88:91]
	v_mfma_f32_16x16x32_bf16 v[80:83], v[218:221], v[194:197], v[80:83]
	v_mfma_f32_16x16x32_bf16 v[72:75], v[210:213], v[202:205], v[72:75]
	v_mfma_f32_16x16x32_bf16 v[64:67], v[218:221], v[202:205], v[64:67]
	s_barrier
	ds_read_b128 v[170:173], v148 offset:16384
	ds_read_b128 v[174:177], v148 offset:17408
	ds_read_b128 v[178:181], v148 offset:18432
	ds_read_b128 v[186:189], v148 offset:19456
	ds_read_b128 v[190:193], v148 offset:20480
	ds_read_b128 v[194:197], v148 offset:21504
	ds_read_b128 v[198:201], v148 offset:22528
	ds_read_b128 v[202:205], v148 offset:23552
	s_add_i32 s53, s44, s34
	v_lshl_add_u64 v[158:159], s[24:25], 0, v[130:131]
	s_mov_b32 m0, s53
	s_nop 0
	global_load_lds_dwordx4 v[158:159], off
	v_lshl_add_u64 v[182:183], s[24:25], 0, v[134:135]
	s_add_i32 m0, s53, 0x2000
	s_nop 0
	global_load_lds_dwordx4 v[182:183], off
	s_mov_b32 m0, s21
	v_lshl_add_u64 v[222:223], s[26:27], 0, v[128:129]
	global_load_lds_dwordx4 v[222:223], off
	v_lshl_add_u64 v[224:225], s[26:27], 0, v[132:133]
	s_mov_b32 m0, s37
	s_nop 0
	global_load_lds_dwordx4 v[224:225], off
	s_add_u32 s54, s24, 0x80000
	s_addc_u32 s55, s25, 0
	s_add_i32 s53, s45, s34
	v_lshl_add_u64 v[230:231], s[54:55], 0, v[130:131]
	s_mov_b32 m0, s53
	s_nop 0
	global_load_lds_dwordx4 v[230:231], off
	v_lshl_add_u64 v[230:231], s[54:55], 0, v[134:135]
	s_add_i32 m0, s53, 0x2000
	s_nop 0
	global_load_lds_dwordx4 v[230:231], off
	s_waitcnt vmcnt(8)
	s_barrier
; #define PG8_STAGE(bufoff, gbase, voff) do { _Pragma("unroll") for (int _i = 0; _i < 2; ++_i) \
;         __builtin_amdgcn_global_load_lds((const unsigned*)((const char*)(gbase) + (voff)[_i]), (LAS unsigned*)(lds + (bufoff) + ldsw + _i * 8192), 16, 0, 0); } while (0)
; #define PG8_LDA(dst, b, h) do { _Pragma("unroll") for (int m = 0; m < 4; ++m) _Pragma("unroll") for (int k = 0; k < 2; ++k) dst[m][k] = *(const LAS bf16x8*)(lds + PG8_SA(b, h) + aoff + m * 2048 + k * 1024); } while (0)
; #define PG8_LDB(dst, b, h) do { _Pragma("unroll") for (int n = 0; n < 2; ++n) _Pragma("unroll") for (int k = 0; k < 2; ++k) dst[n][k] = *(const LAS bf16x8*)(lds + PG8_SB(b, h) + boff + n * 2048 + k * 1024); } while (0)
; #define PG8_WAIT_V(n) asm volatile("s_waitcnt vmcnt(" #n ")" ::: "memory")
; #define PG8_WAIT_L(n) asm volatile("s_waitcnt lgkmcnt(" #n ")" ::: "memory")
; template <class Epi, class Sched>
; __device__ __forceinline__ void gemm_phase(LAS unsigned char* lds, const Gemm g, const Sched& S, const Epi& E) {
;     ...
;             PG8_LDB(B0, 0, 0); PG8_SCHED; PG8_LDA(At, 0, 0); PG8_STAGE(PG8_SA(1, 1), a1 + hstepA, voffA);
;             PG8_WAIT_L(8); PG8_BAR; PG8_WAIT_L(0); PG8_MMA(0, 0, At, B0); PG8_BAR; PG8_SCHED;
;             PG8_LDB(B1, 0, 1); PG8_STAGE(PG8_SB(0, 0), b2, voffB);
;             PG8_BAR; PG8_WAIT_L(0); if constexpr (!Epi::DIAG) PG8_MMA(0, 1, At, B1); PG8_BAR;
;             PG8_LDA(At, 0, 1); PG8_STAGE(PG8_SA(0, 0), a2, voffA);
;             PG8_BAR; PG8_WAIT_L(0); if constexpr (!Epi::DIAG) PG8_MMA(1, 0, At, B0); PG8_BAR; PG8_SCHED;
;             PG8_STAGE(PG8_SB(0, 1), b2 + hstepB, voffB);
;             PG8_WAIT_V(6); PG8_BAR; PG8_MMA(1, 1, At, B1); PG8_BAR;
;             PG8_LDB(B0, 1, 0); PG8_SCHED; PG8_LDA(At, 1, 0); PG8_STAGE(PG8_SA(0, 1), a2 + hstepA, voffA);
;             PG8_WAIT_L(8); PG8_BAR; PG8_WAIT_L(0); PG8_MMA(0, 0, At, B0); PG8_BAR; PG8_SCHED;
;             PG8_LDB(B1, 1, 1); PG8_STAGE(PG8_SB(1, 0), b3, voffB);
;             PG8_BAR; PG8_WAIT_L(0); if constexpr (!Epi::DIAG) PG8_MMA(0, 1, At, B1); PG8_BAR;
;             PG8_LDA(At, 1, 1); PG8_STAGE(PG8_SA(1, 0), a3, voffA);
;             PG8_BAR; PG8_WAIT_L(0); if constexpr (!Epi::DIAG) PG8_MMA(1, 0, At, B0); PG8_BAR; PG8_SCHED;
;             PG8_STAGE(PG8_SB(1, 1), b3 + hstepB, voffB);
;             PG8_WAIT_V(6); PG8_BAR; PG8_MMA(1, 1, At, B1); PG8_BAR;
	s_waitcnt lgkmcnt(0)
	v_mfma_f32_16x16x32_bf16 v[60:63], v[150:153], v[170:173], v[60:63]
	v_mfma_f32_16x16x32_bf16 v[52:55], v[162:165], v[170:173], v[52:55]
	v_mfma_f32_16x16x32_bf16 v[44:47], v[150:153], v[178:181], v[44:47]
	v_mfma_f32_16x16x32_bf16 v[36:39], v[162:165], v[178:181], v[36:39]
	v_mfma_f32_16x16x32_bf16 v[28:31], v[150:153], v[190:193], v[28:31]
	v_mfma_f32_16x16x32_bf16 v[20:23], v[162:165], v[190:193], v[20:23]
	v_mfma_f32_16x16x32_bf16 v[12:15], v[150:153], v[198:201], v[12:15]
	v_mfma_f32_16x16x32_bf16 v[4:7], v[162:165], v[198:201], v[4:7]
	v_mfma_f32_16x16x32_bf16 v[60:63], v[154:157], v[174:177], v[60:63]
	v_mfma_f32_16x16x32_bf16 v[52:55], v[166:169], v[174:177], v[52:55]
	v_mfma_f32_16x16x32_bf16 v[44:47], v[154:157], v[186:189], v[44:47]
	v_mfma_f32_16x16x32_bf16 v[36:39], v[166:169], v[186:189], v[36:39]
	v_mfma_f32_16x16x32_bf16 v[28:31], v[154:157], v[194:197], v[28:31]
	v_mfma_f32_16x16x32_bf16 v[20:23], v[166:169], v[194:197], v[20:23]
	v_mfma_f32_16x16x32_bf16 v[12:15], v[154:157], v[202:205], v[12:15]
	v_mfma_f32_16x16x32_bf16 v[4:7], v[166:169], v[202:205], v[4:7]
	v_mfma_f32_16x16x32_bf16 v[56:59], v[206:209], v[170:173], v[56:59]
	v_mfma_f32_16x16x32_bf16 v[48:51], v[214:217], v[170:173], v[48:51]
	v_mfma_f32_16x16x32_bf16 v[40:43], v[206:209], v[178:181], v[40:43]
	v_mfma_f32_16x16x32_bf16 v[32:35], v[214:217], v[178:181], v[32:35]
	v_mfma_f32_16x16x32_bf16 v[24:27], v[206:209], v[190:193], v[24:27]
	v_mfma_f32_16x16x32_bf16 v[16:19], v[214:217], v[190:193], v[16:19]
	v_mfma_f32_16x16x32_bf16 v[8:11], v[206:209], v[198:201], v[8:11]
	v_mfma_f32_16x16x32_bf16 v[0:3], v[214:217], v[198:201], v[0:3]
	v_mfma_f32_16x16x32_bf16 v[56:59], v[210:213], v[174:177], v[56:59]
	v_mfma_f32_16x16x32_bf16 v[48:51], v[218:221], v[174:177], v[48:51]
	v_mfma_f32_16x16x32_bf16 v[40:43], v[210:213], v[186:189], v[40:43]
	v_mfma_f32_16x16x32_bf16 v[32:35], v[218:221], v[186:189], v[32:35]
	v_mfma_f32_16x16x32_bf16 v[24:27], v[210:213], v[194:197], v[24:27]
	v_mfma_f32_16x16x32_bf16 v[16:19], v[218:221], v[194:197], v[16:19]
	v_mfma_f32_16x16x32_bf16 v[8:11], v[210:213], v[202:205], v[8:11]
	v_mfma_f32_16x16x32_bf16 v[0:3], v[218:221], v[202:205], v[0:3]
	s_barrier
	s_add_i32 s53, 0, 0x18000
	v_add_u32_e32 v161, s53, v145
	ds_read_b128 v[150:153], v161
	ds_read_b128 v[154:157], v161 offset:1024
	ds_read_b128 v[162:165], v161 offset:2048
	ds_read_b128 v[166:169], v161 offset:3072
	ds_read_b128 v[170:173], v148 offset:32768
	ds_read_b128 v[174:177], v148 offset:33792
	ds_read_b128 v[178:181], v148 offset:34816
	ds_read_b128 v[186:189], v148 offset:35840
	ds_read_b128 v[190:193], v148 offset:36864
	ds_read_b128 v[194:197], v148 offset:37888
	ds_read_b128 v[198:201], v148 offset:38912
	ds_read_b128 v[202:205], v148 offset:39936
	s_add_u32 s26, s26, 0x80000
	s_addc_u32 s27, s27, 0
	s_mov_b32 m0, s38
	v_lshl_add_u64 v[230:231], s[26:27], 0, v[128:129]
	global_load_lds_dwordx4 v[230:231], off
	v_lshl_add_u64 v[230:231], s[26:27], 0, v[132:133]
	s_mov_b32 m0, s39
	s_nop 0
	global_load_lds_dwordx4 v[230:231], off
	s_add_i32 s26, 0, 0x1c000
	s_add_i32 s27, s53, s34
	v_add_u32_e32 v161, s26, v145
	ds_read_b128 v[206:209], v161
	ds_read_b128 v[210:213], v161 offset:1024
	ds_read_b128 v[214:217], v161 offset:2048
	ds_read_b128 v[218:221], v161 offset:3072
	s_waitcnt vmcnt(8)
	s_barrier
	s_waitcnt lgkmcnt(0)
	v_mfma_f32_16x16x32_bf16 v[124:127], v[150:153], v[170:173], v[124:127]
	v_mfma_f32_16x16x32_bf16 v[116:119], v[162:165], v[170:173], v[116:119]
	v_mfma_f32_16x16x32_bf16 v[108:111], v[150:153], v[178:181], v[108:111]
	v_mfma_f32_16x16x32_bf16 v[100:103], v[162:165], v[178:181], v[100:103]
	v_mfma_f32_16x16x32_bf16 v[92:95], v[150:153], v[190:193], v[92:95]
	v_mfma_f32_16x16x32_bf16 v[84:87], v[162:165], v[190:193], v[84:87]
	v_mfma_f32_16x16x32_bf16 v[76:79], v[150:153], v[198:201], v[76:79]
	v_mfma_f32_16x16x32_bf16 v[68:71], v[162:165], v[198:201], v[68:71]
	v_mfma_f32_16x16x32_bf16 v[124:127], v[154:157], v[174:177], v[124:127]
	v_mfma_f32_16x16x32_bf16 v[116:119], v[166:169], v[174:177], v[116:119]
	v_mfma_f32_16x16x32_bf16 v[108:111], v[154:157], v[186:189], v[108:111]
	v_mfma_f32_16x16x32_bf16 v[100:103], v[166:169], v[186:189], v[100:103]
	v_mfma_f32_16x16x32_bf16 v[92:95], v[154:157], v[194:197], v[92:95]
	v_mfma_f32_16x16x32_bf16 v[84:87], v[166:169], v[194:197], v[84:87]
	v_mfma_f32_16x16x32_bf16 v[76:79], v[154:157], v[202:205], v[76:79]
	v_mfma_f32_16x16x32_bf16 v[68:71], v[166:169], v[202:205], v[68:71]
	v_mfma_f32_16x16x32_bf16 v[120:123], v[206:209], v[170:173], v[120:123]
	v_mfma_f32_16x16x32_bf16 v[112:115], v[214:217], v[170:173], v[112:115]
	v_mfma_f32_16x16x32_bf16 v[104:107], v[206:209], v[178:181], v[104:107]
	v_mfma_f32_16x16x32_bf16 v[96:99], v[214:217], v[178:181], v[96:99]
	v_mfma_f32_16x16x32_bf16 v[88:91], v[206:209], v[190:193], v[88:91]
	v_mfma_f32_16x16x32_bf16 v[80:83], v[214:217], v[190:193], v[80:83]
	v_mfma_f32_16x16x32_bf16 v[72:75], v[206:209], v[198:201], v[72:75]
	v_mfma_f32_16x16x32_bf16 v[64:67], v[214:217], v[198:201], v[64:67]
	v_mfma_f32_16x16x32_bf16 v[120:123], v[210:213], v[174:177], v[120:123]
	v_mfma_f32_16x16x32_bf16 v[112:115], v[218:221], v[174:177], v[112:115]
	v_mfma_f32_16x16x32_bf16 v[104:107], v[210:213], v[186:189], v[104:107]
	v_mfma_f32_16x16x32_bf16 v[96:99], v[218:221], v[186:189], v[96:99]
	v_mfma_f32_16x16x32_bf16 v[88:91], v[210:213], v[194:197], v[88:91]
	v_mfma_f32_16x16x32_bf16 v[80:83], v[218:221], v[194:197], v[80:83]
	v_mfma_f32_16x16x32_bf16 v[72:75], v[210:213], v[202:205], v[72:75]
	v_mfma_f32_16x16x32_bf16 v[64:67], v[218:221], v[202:205], v[64:67]
	s_barrier
; #define PG8_STAGE(bufoff, gbase, voff) do { _Pragma("unroll") for (int _i = 0; _i < 2; ++_i) \
;         __builtin_amdgcn_global_load_lds((const unsigned*)((const char*)(gbase) + (voff)[_i]), (LAS unsigned*)(lds + (bufoff) + ldsw + _i * 8192), 16, 0, 0); } while (0)
; #define PG8_LDA(dst, b, h) do { _Pragma("unroll") for (int m = 0; m < 4; ++m) _Pragma("unroll") for (int k = 0; k < 2; ++k) dst[m][k] = *(const LAS bf16x8*)(lds + PG8_SA(b, h) + aoff + m * 2048 + k * 1024); } while (0)
; #define PG8_LDB(dst, b, h) do { _Pragma("unroll") for (int n = 0; n < 2; ++n) _Pragma("unroll") for (int k = 0; k < 2; ++k) dst[n][k] = *(const LAS bf16x8*)(lds + PG8_SB(b, h) + boff + n * 2048 + k * 1024); } while (0)
; #define PG8_WAIT_V(n) asm volatile("s_waitcnt vmcnt(" #n ")" ::: "memory")
; #define PG8_WAIT_L(n) asm volatile("s_waitcnt lgkmcnt(" #n ")" ::: "memory")
; template <class Epi, class Sched>
; __device__ __forceinline__ void gemm_phase(LAS unsigned char* lds, const Gemm g, const Sched& S, const Epi& E) {
;     ...
;             PG8_LDB(B0, 1, 0); PG8_SCHED; PG8_LDA(At, 1, 0); PG8_STAGE(PG8_SA(0, 1), a2 + hstepA, voffA);
;             PG8_WAIT_L(8); PG8_BAR; PG8_WAIT_L(0); PG8_MMA(0, 0, At, B0); PG8_BAR; PG8_SCHED;
;             PG8_LDB(B1, 1, 1); PG8_STAGE(PG8_SB(1, 0), b3, voffB);
;             PG8_BAR; PG8_WAIT_L(0); if constexpr (!Epi::DIAG) PG8_MMA(0, 1, At, B1); PG8_BAR;
;             PG8_LDA(At, 1, 1); PG8_STAGE(PG8_SA(1, 0), a3, voffA);
;             PG8_BAR; PG8_WAIT_L(0); if constexpr (!Epi::DIAG) PG8_MMA(1, 0, At, B0); PG8_BAR; PG8_SCHED;
;             PG8_STAGE(PG8_SB(1, 1), b3 + hstepB, voffB);
;             PG8_WAIT_V(6); PG8_BAR; PG8_MMA(1, 1, At, B1); PG8_BAR;
;     __device__ __forceinline__ void operator()(const Acc& acc, const Unit& u, int wr, int wc, int fr, int fq) const {
;         const int row0 = u.pm * BM + wr * 64 + fr, col0 = u.pn * HALF + wc * 32 + 8 * fq;
; #pragma unroll
;         for (int ai = 0; ai < 2; ++ai)
; #pragma unroll
;             for (int m = 0; m < 4; ++m) { float v[8];
; #pragma unroll
;                 for (int n = 0; n < 2; ++n) {
;                     const f32x4 gt = acc[ai][0][m][n], arg = gt * (-1.4426950408889634f), gu = gt * acc[ai][1][m][n];
;                     f32x4 t;
; #pragma unroll
;                     for (int j = 0; j < 4; ++j) t[j] = __builtin_amdgcn_exp2f(arg[j]);
	ds_read_b128 v[170:173], v148 offset:49152
	ds_read_b128 v[174:177], v148 offset:50176
	ds_read_b128 v[178:181], v148 offset:51200
	ds_read_b128 v[186:189], v148 offset:52224
	ds_read_b128 v[190:193], v148 offset:53248
	ds_read_b128 v[194:197], v148 offset:54272
	ds_read_b128 v[198:201], v148 offset:55296
	ds_read_b128 v[202:205], v148 offset:56320
	v_lshl_add_u64 v[158:159], v[158:159], 0, s[10:11]
	s_mov_b32 m0, s27
	s_nop 0
	global_load_lds_dwordx4 v[158:159], off
	v_lshl_add_u64 v[158:159], v[182:183], 0, s[10:11]
	s_add_i32 m0, s27, 0x2000
	s_nop 0
	global_load_lds_dwordx4 v[158:159], off
	s_mov_b32 m0, s42
	v_lshl_add_u64 v[158:159], v[222:223], 0, s[10:11]
	global_load_lds_dwordx4 v[158:159], off
	v_lshl_add_u64 v[158:159], v[224:225], 0, s[10:11]
	s_mov_b32 m0, s43
	s_nop 0
	global_load_lds_dwordx4 v[158:159], off
	s_add_u32 s24, s24, 0x80080
	s_addc_u32 s25, s25, 0
	s_add_i32 s26, s26, s34
	v_lshl_add_u64 v[230:231], s[24:25], 0, v[130:131]
	s_mov_b32 m0, s26
	s_nop 0
	global_load_lds_dwordx4 v[230:231], off
	v_lshl_add_u64 v[230:231], s[24:25], 0, v[134:135]
	s_add_i32 m0, s26, 0x2000
	s_nop 0
	global_load_lds_dwordx4 v[230:231], off
	s_waitcnt vmcnt(8)
	s_barrier
	s_waitcnt lgkmcnt(0)
	v_mfma_f32_16x16x32_bf16 v[60:63], v[150:153], v[170:173], v[60:63]
	v_mfma_f32_16x16x32_bf16 v[52:55], v[162:165], v[170:173], v[52:55]
	v_mfma_f32_16x16x32_bf16 v[44:47], v[150:153], v[178:181], v[44:47]
	v_mfma_f32_16x16x32_bf16 v[36:39], v[162:165], v[178:181], v[36:39]
	v_mfma_f32_16x16x32_bf16 v[28:31], v[150:153], v[190:193], v[28:31]
	v_mfma_f32_16x16x32_bf16 v[20:23], v[162:165], v[190:193], v[20:23]
	v_mfma_f32_16x16x32_bf16 v[12:15], v[150:153], v[198:201], v[12:15]
	v_mfma_f32_16x16x32_bf16 v[4:7], v[162:165], v[198:201], v[4:7]
	v_mfma_f32_16x16x32_bf16 v[60:63], v[154:157], v[174:177], v[60:63]
	v_mfma_f32_16x16x32_bf16 v[52:55], v[166:169], v[174:177], v[52:55]
	v_mfma_f32_16x16x32_bf16 v[44:47], v[154:157], v[186:189], v[44:47]
	v_mfma_f32_16x16x32_bf16 v[36:39], v[166:169], v[186:189], v[36:39]
	v_mfma_f32_16x16x32_bf16 v[28:31], v[154:157], v[194:197], v[28:31]
	v_mfma_f32_16x16x32_bf16 v[20:23], v[166:169], v[194:197], v[20:23]
	v_mfma_f32_16x16x32_bf16 v[12:15], v[154:157], v[202:205], v[12:15]
	v_mfma_f32_16x16x32_bf16 v[4:7], v[166:169], v[202:205], v[4:7]
	v_mfma_f32_16x16x32_bf16 v[56:59], v[206:209], v[170:173], v[56:59]
	v_mfma_f32_16x16x32_bf16 v[48:51], v[214:217], v[170:173], v[48:51]
	v_mfma_f32_16x16x32_bf16 v[40:43], v[206:209], v[178:181], v[40:43]
	v_mfma_f32_16x16x32_bf16 v[32:35], v[214:217], v[178:181], v[32:35]
	v_mfma_f32_16x16x32_bf16 v[24:27], v[206:209], v[190:193], v[24:27]
	v_mfma_f32_16x16x32_bf16 v[16:19], v[214:217], v[190:193], v[16:19]
	v_mfma_f32_16x16x32_bf16 v[8:11], v[206:209], v[198:201], v[8:11]
	v_mfma_f32_16x16x32_bf16 v[0:3], v[214:217], v[198:201], v[0:3]
	v_mfma_f32_16x16x32_bf16 v[56:59], v[210:213], v[174:177], v[56:59]
	v_mfma_f32_16x16x32_bf16 v[48:51], v[218:221], v[174:177], v[48:51]
	v_mfma_f32_16x16x32_bf16 v[40:43], v[210:213], v[186:189], v[40:43]
	v_mfma_f32_16x16x32_bf16 v[32:35], v[218:221], v[186:189], v[32:35]
	v_mfma_f32_16x16x32_bf16 v[24:27], v[210:213], v[194:197], v[24:27]
	v_mfma_f32_16x16x32_bf16 v[16:19], v[218:221], v[194:197], v[16:19]
	v_mfma_f32_16x16x32_bf16 v[8:11], v[210:213], v[202:205], v[8:11]
	v_mfma_f32_16x16x32_bf16 v[0:3], v[218:221], v[202:205], v[0:3]
	s_add_i32 s52, s52, 2
	s_add_u32 s22, s22, 0x100
	s_addc_u32 s23, s23, 0
	s_add_u32 s50, s50, 0x100
	s_addc_u32 s51, s51, 0
	s_cmp_gt_u32 s52, 29
	s_barrier
	s_cbranch_scc0 .LBB0_1843
	s_setprio 0
	v_mul_f32_e32 v153, 0xbfb8aa3b, v126
	v_exp_f32_e32 v154, v153
	v_mul_f32_e32 v153, 0xbfb8aa3b, v127
	v_mul_f32_e32 v151, 0xbfb8aa3b, v124
	v_exp_f32_e32 v155, v153
	v_exp_f32_e32 v152, v151
	v_mul_f32_e32 v151, 0xbfb8aa3b, v125
	v_pk_mul_f32 v[120:121], v[120:121], v[124:125]
	v_mul_f32_e32 v124, 0xbfb8aa3b, v116
	v_mul_f32_e32 v125, 0xbfb8aa3b, v117
	v_pk_mul_f32 v[122:123], v[122:123], v[126:127]
	v_exp_f32_e32 v124, v124
	v_mul_f32_e32 v126, 0xbfb8aa3b, v118
	v_mul_f32_e32 v127, 0xbfb8aa3b, v119
	v_exp_f32_e32 v125, v125
	v_exp_f32_e32 v153, v151
	v_exp_f32_e32 v126, v126
	v_exp_f32_e32 v127, v127
	v_pk_add_f32 v[154:155], v[154:155], 1.0 op_sel_hi:[1,0]
	v_pk_add_f32 v[124:125], v[124:125], 1.0 op_sel_hi:[1,0]
	v_rcp_f32_e32 v154, v154
	v_rcp_f32_e32 v155, v155
	v_pk_add_f32 v[152:153], v[152:153], 1.0 op_sel_hi:[1,0]
	v_pk_add_f32 v[126:127], v[126:127], 1.0 op_sel_hi:[1,0]
	v_rcp_f32_e32 v124, v124
	v_rcp_f32_e32 v125, v125
	v_rcp_f32_e32 v152, v152
	v_rcp_f32_e32 v153, v153
	v_rcp_f32_e32 v126, v126
	v_rcp_f32_e32 v127, v127
	v_pk_mul_f32 v[122:123], v[122:123], v[154:155]
	v_pk_mul_f32 v[112:113], v[112:113], v[116:117]
	v_cvt_pk_bf16_f32 v117, v122, v123
	v_mul_f32_e32 v122, 0xbfb8aa3b, v108
	v_mul_f32_e32 v123, 0xbfb8aa3b, v109
	v_lshl_or_b32 v156, s47, 7, v146
	v_pk_mul_f32 v[114:115], v[114:115], v[118:119]
	v_pk_mul_f32 v[112:113], v[112:113], v[124:125]
	v_exp_f32_e32 v122, v122
	v_mul_f32_e32 v124, 0xbfb8aa3b, v110
	v_mul_f32_e32 v125, 0xbfb8aa3b, v111
	v_exp_f32_e32 v123, v123
	v_pk_mul_f32 v[106:107], v[106:107], v[110:111]
	v_pk_mul_f32 v[104:105], v[104:105], v[108:109]
	v_mul_f32_e32 v108, 0xbfb8aa3b, v100
	v_mul_f32_e32 v109, 0xbfb8aa3b, v101
	v_mul_f32_e32 v110, 0xbfb8aa3b, v102
	v_mul_f32_e32 v111, 0xbfb8aa3b, v103
	v_lshl_add_u32 v150, s20, 8, v144
	v_ashrrev_i32_e32 v157, 31, v156
	v_pk_mul_f32 v[120:121], v[120:121], v[152:153]
	v_pk_mul_f32 v[114:115], v[114:115], v[126:127]
	v_cvt_pk_bf16_f32 v118, v112, v113
	v_mov_b64_e32 v[112:113], s[8:9]
	v_exp_f32_e32 v108, v108
; __device__ __forceinline__ u32x4 pack8(const float* f) { u32x4 w; w.x = pk2(f[0], f[1]); w.y = pk2(f[2], f[3]); w.z = pk2(f[4], f[5]); w.w = pk2(f[6], f[7]); return w; }
;     __device__ __forceinline__ void operator()(const Acc& acc, const Unit& u, int wr, int wc, int fr, int fq) const { if (u.piece == 0) e1(acc, u, wr, wc, fr, fq); else e2(acc, u, wr, wc, fr, fq); }
;     __device__ __forceinline__ void operator()(const Acc& acc, const Unit& u, int wr, int wc, int fr, int fq) const {
;         const int row0 = u.pm * BM + wr * 64 + fr, col0 = u.pn * HALF + wc * 32 + 8 * fq;
; #pragma unroll
;         for (int ai = 0; ai < 2; ++ai)
; #pragma unroll
;             for (int m = 0; m < 4; ++m) { float v[8];
; #pragma unroll
;                 for (int n = 0; n < 2; ++n) {
;                     const f32x4 gt = acc[ai][0][m][n], arg = gt * (-1.4426950408889634f), gu = gt * acc[ai][1][m][n];
;                     f32x4 t;
; #pragma unroll
;                     for (int j = 0; j < 4; ++j) t[j] = __builtin_amdgcn_exp2f(arg[j]);
;                     t = t + 1.0f;
; #pragma unroll
;                     for (int j = 0; j < 4; ++j) t[j] = __builtin_amdgcn_rcpf(t[j]);
;                     const f32x4 r = gu * t;
; #pragma unroll
;                     for (int j = 0; j < 4; ++j) v[4 * n + j] = r[j]; }
;                 *(u32x4*)(O + (size_t)(row0 + ai * HALF + m * 16) * DFF + col0) = pack8(v); }
;     }
	v_exp_f32_e32 v110, v110
	v_exp_f32_e32 v111, v111
	v_exp_f32_e32 v109, v109
	v_cvt_pk_bf16_f32 v116, v120, v121
	v_cvt_pk_bf16_f32 v119, v114, v115
	v_mad_i64_i32 v[120:121], s[22:23], v150, s46, v[112:113]
	v_lshlrev_b64 v[114:115], 1, v[156:157]
	v_lshl_add_u64 v[120:121], v[120:121], 0, v[114:115]
	global_store_dwordx4 v[120:121], v[116:119], off
	v_exp_f32_e32 v124, v124
	v_exp_f32_e32 v125, v125
	v_pk_add_f32 v[118:119], v[122:123], 1.0 op_sel_hi:[1,0]
	v_pk_add_f32 v[110:111], v[110:111], 1.0 op_sel_hi:[1,0]
	v_rcp_f32_e32 v118, v118
	v_rcp_f32_e32 v119, v119
	v_pk_add_f32 v[108:109], v[108:109], 1.0 op_sel_hi:[1,0]
	v_rcp_f32_e32 v110, v110
	v_rcp_f32_e32 v108, v108
	v_rcp_f32_e32 v109, v109
	v_rcp_f32_e32 v111, v111
	v_pk_add_f32 v[116:117], v[124:125], 1.0 op_sel_hi:[1,0]
	v_pk_mul_f32 v[104:105], v[104:105], v[118:119]
	v_pk_mul_f32 v[98:99], v[98:99], v[102:103]
	v_pk_mul_f32 v[96:97], v[96:97], v[100:101]
	v_rcp_f32_e32 v116, v116
	v_rcp_f32_e32 v117, v117
	v_pk_mul_f32 v[100:101], v[96:97], v[108:109]
	v_pk_mul_f32 v[102:103], v[98:99], v[110:111]
	v_cvt_pk_bf16_f32 v96, v104, v105
	v_mul_f32_e32 v104, 0xbfb8aa3b, v94
	v_mul_f32_e32 v105, 0xbfb8aa3b, v95
	v_pk_mul_f32 v[90:91], v[90:91], v[94:95]
	v_mul_f32_e32 v94, 0xbfb8aa3b, v86
	v_mul_f32_e32 v95, 0xbfb8aa3b, v87
	v_cvt_pk_bf16_f32 v99, v102, v103
	v_mul_f32_e32 v102, 0xbfb8aa3b, v92
	v_mul_f32_e32 v103, 0xbfb8aa3b, v93
	v_exp_f32_e32 v94, v94
	v_exp_f32_e32 v95, v95
	v_exp_f32_e32 v102, v102
	v_exp_f32_e32 v103, v103
	v_pk_mul_f32 v[88:89], v[88:89], v[92:93]
	v_mul_f32_e32 v92, 0xbfb8aa3b, v84
	v_mul_f32_e32 v93, 0xbfb8aa3b, v85
	v_cvt_pk_bf16_f32 v98, v100, v101
	v_or_b32_e32 v100, 16, v150
	v_exp_f32_e32 v92, v92
	v_exp_f32_e32 v93, v93
	v_pk_mul_f32 v[106:107], v[106:107], v[116:117]
	v_mad_i64_i32 v[100:101], s[22:23], v100, s46, v[112:113]
	v_cvt_pk_bf16_f32 v97, v106, v107
	v_exp_f32_e32 v104, v104
	v_exp_f32_e32 v105, v105
	v_lshl_add_u64 v[100:101], v[100:101], 0, v[114:115]
	v_pk_add_f32 v[94:95], v[94:95], 1.0 op_sel_hi:[1,0]
	global_store_dwordx4 v[100:101], v[96:99], off
	v_rcp_f32_e32 v94, v94
	v_rcp_f32_e32 v95, v95
	v_pk_add_f32 v[98:99], v[102:103], 1.0 op_sel_hi:[1,0]
	v_pk_add_f32 v[92:93], v[92:93], 1.0 op_sel_hi:[1,0]
	v_rcp_f32_e32 v98, v98
	v_rcp_f32_e32 v99, v99
	v_rcp_f32_e32 v92, v92
	v_rcp_f32_e32 v93, v93
	v_pk_add_f32 v[96:97], v[104:105], 1.0 op_sel_hi:[1,0]
	v_pk_mul_f32 v[82:83], v[82:83], v[86:87]
	v_rcp_f32_e32 v96, v96
	v_rcp_f32_e32 v97, v97
	v_pk_mul_f32 v[86:87], v[82:83], v[94:95]
	v_pk_mul_f32 v[88:89], v[88:89], v[98:99]
	v_pk_mul_f32 v[80:81], v[80:81], v[84:85]
	v_cvt_pk_bf16_f32 v83, v86, v87
	v_mul_f32_e32 v86, 0xbfb8aa3b, v76
	v_mul_f32_e32 v87, 0xbfb8aa3b, v77
	v_pk_mul_f32 v[84:85], v[80:81], v[92:93]
	v_cvt_pk_bf16_f32 v80, v88, v89
	v_exp_f32_e32 v86, v86
	v_mul_f32_e32 v88, 0xbfb8aa3b, v78
	v_mul_f32_e32 v89, 0xbfb8aa3b, v79
	v_exp_f32_e32 v87, v87
	v_pk_mul_f32 v[74:75], v[74:75], v[78:79]
	v_pk_mul_f32 v[72:73], v[72:73], v[76:77]
	v_mul_f32_e32 v76, 0xbfb8aa3b, v68
	v_mul_f32_e32 v77, 0xbfb8aa3b, v69
	v_mul_f32_e32 v78, 0xbfb8aa3b, v70
	v_mul_f32_e32 v79, 0xbfb8aa3b, v71
	v_cvt_pk_bf16_f32 v82, v84, v85
	v_or_b32_e32 v84, 32, v150
	v_exp_f32_e32 v76, v76
	v_exp_f32_e32 v78, v78
	v_exp_f32_e32 v79, v79
	v_exp_f32_e32 v77, v77
	v_pk_mul_f32 v[90:91], v[90:91], v[96:97]
	v_mad_i64_i32 v[84:85], s[22:23], v84, s46, v[112:113]
	v_cvt_pk_bf16_f32 v81, v90, v91
	v_lshl_add_u64 v[84:85], v[84:85], 0, v[114:115]
	global_store_dwordx4 v[84:85], v[80:83], off
	v_exp_f32_e32 v88, v88
	v_exp_f32_e32 v89, v89
	v_pk_add_f32 v[82:83], v[86:87], 1.0 op_sel_hi:[1,0]
	v_pk_add_f32 v[78:79], v[78:79], 1.0 op_sel_hi:[1,0]
	v_rcp_f32_e32 v82, v82
	v_rcp_f32_e32 v83, v83
	v_pk_add_f32 v[76:77], v[76:77], 1.0 op_sel_hi:[1,0]
	v_rcp_f32_e32 v78, v78
	v_rcp_f32_e32 v76, v76
	v_rcp_f32_e32 v77, v77
	v_rcp_f32_e32 v79, v79
	v_pk_add_f32 v[80:81], v[88:89], 1.0 op_sel_hi:[1,0]
	v_pk_mul_f32 v[72:73], v[72:73], v[82:83]
	v_pk_mul_f32 v[66:67], v[66:67], v[70:71]
	v_pk_mul_f32 v[64:65], v[64:65], v[68:69]
	v_rcp_f32_e32 v80, v80
	v_rcp_f32_e32 v81, v81
	v_pk_mul_f32 v[68:69], v[64:65], v[76:77]
	v_pk_mul_f32 v[70:71], v[66:67], v[78:79]
	v_cvt_pk_bf16_f32 v64, v72, v73
	v_mul_f32_e32 v72, 0xbfb8aa3b, v62
	v_mul_f32_e32 v73, 0xbfb8aa3b, v63
	v_pk_mul_f32 v[58:59], v[58:59], v[62:63]
	v_mul_f32_e32 v62, 0xbfb8aa3b, v54
	v_mul_f32_e32 v63, 0xbfb8aa3b, v55
	v_cvt_pk_bf16_f32 v67, v70, v71
	v_mul_f32_e32 v70, 0xbfb8aa3b, v60
	v_mul_f32_e32 v71, 0xbfb8aa3b, v61
	v_exp_f32_e32 v62, v62
	v_exp_f32_e32 v63, v63
	v_exp_f32_e32 v70, v70
	v_exp_f32_e32 v71, v71
	v_pk_mul_f32 v[56:57], v[56:57], v[60:61]
	v_mul_f32_e32 v60, 0xbfb8aa3b, v52
	v_mul_f32_e32 v61, 0xbfb8aa3b, v53
	v_cvt_pk_bf16_f32 v66, v68, v69
	v_or_b32_e32 v68, 48, v150
	v_exp_f32_e32 v60, v60
	v_exp_f32_e32 v61, v61
	v_pk_mul_f32 v[74:75], v[74:75], v[80:81]
	v_mad_i64_i32 v[68:69], s[22:23], v68, s46, v[112:113]
	v_cvt_pk_bf16_f32 v65, v74, v75
	v_lshl_add_u64 v[68:69], v[68:69], 0, v[114:115]
	v_exp_f32_e32 v72, v72
	v_exp_f32_e32 v73, v73
	v_pk_add_f32 v[62:63], v[62:63], 1.0 op_sel_hi:[1,0]
	global_store_dwordx4 v[68:69], v[64:67], off
	v_rcp_f32_e32 v62, v62
	v_rcp_f32_e32 v63, v63
	v_pk_add_f32 v[66:67], v[70:71], 1.0 op_sel_hi:[1,0]
	v_pk_add_f32 v[60:61], v[60:61], 1.0 op_sel_hi:[1,0]
	v_rcp_f32_e32 v66, v66
	v_rcp_f32_e32 v67, v67
	v_rcp_f32_e32 v60, v60
	v_rcp_f32_e32 v61, v61
	v_pk_add_f32 v[64:65], v[72:73], 1.0 op_sel_hi:[1,0]
; __device__ __forceinline__ u32x4 pack8(const float* f) { u32x4 w; w.x = pk2(f[0], f[1]); w.y = pk2(f[2], f[3]); w.z = pk2(f[4], f[5]); w.w = pk2(f[6], f[7]); return w; }
; #define PG8_WAIT_V(n) asm volatile("s_waitcnt vmcnt(" #n ")" ::: "memory")
; #define PG8_BAR __builtin_amdgcn_s_barrier()
; template <class Epi, class Sched>
; __device__ __forceinline__ void gemm_phase(LAS unsigned char* lds, const Gemm g, const Sched& S, const Epi& E) {
;     ...
;         E(acc, cur, wr, wc, fr, fq);
;         if (!has_next) break;
; #pragma unroll
;         for (int a = 0; a < 2; ++a)
; #pragma unroll
;             for (int b = 0; b < 2; ++b)
; #pragma unroll
;                 for (int m = 0; m < 4; ++m)
; #pragma unroll
;                     for (int n = 0; n < 2; ++n) acc[a][b][m][n] = (f32x4){0.f, 0.f, 0.f, 0.f};
;         cur = nxt; cA = nA; cB = nB; ++ui;
;     }
;     PG8_WAIT_V(0);
;     if (wr == 0) PG8_BAR;
;     __device__ __forceinline__ void operator()(const Acc& acc, const Unit& u, int wr, int wc, int fr, int fq) const {
;     ...
;             for (int m = 0; m < 4; ++m) { float v[8];
; #pragma unroll
;                 for (int n = 0; n < 2; ++n) {
;                     const f32x4 gt = acc[ai][0][m][n], arg = gt * (-1.4426950408889634f), gu = gt * acc[ai][1][m][n];
;                     f32x4 t;
; #pragma unroll
;                     for (int j = 0; j < 4; ++j) t[j] = __builtin_amdgcn_exp2f(arg[j]);
;                     t = t + 1.0f;
; #pragma unroll
;                     for (int j = 0; j < 4; ++j) t[j] = __builtin_amdgcn_rcpf(t[j]);
;                     const f32x4 r = gu * t;
; #pragma unroll
;                     for (int j = 0; j < 4; ++j) v[4 * n + j] = r[j]; }
;                 *(u32x4*)(O + (size_t)(row0 + ai * HALF + m * 16) * DFF + col0) = pack8(v); }
	v_pk_mul_f32 v[50:51], v[50:51], v[54:55]
	v_rcp_f32_e32 v64, v64
	v_rcp_f32_e32 v65, v65
	v_pk_mul_f32 v[54:55], v[50:51], v[62:63]
	v_pk_mul_f32 v[56:57], v[56:57], v[66:67]
	v_pk_mul_f32 v[48:49], v[48:49], v[52:53]
	v_cvt_pk_bf16_f32 v51, v54, v55
	v_mul_f32_e32 v54, 0xbfb8aa3b, v44
	v_mul_f32_e32 v55, 0xbfb8aa3b, v45
	v_pk_mul_f32 v[52:53], v[48:49], v[60:61]
	v_cvt_pk_bf16_f32 v48, v56, v57
	v_exp_f32_e32 v54, v54
	v_mul_f32_e32 v56, 0xbfb8aa3b, v46
	v_mul_f32_e32 v57, 0xbfb8aa3b, v47
	v_exp_f32_e32 v55, v55
	v_pk_mul_f32 v[42:43], v[42:43], v[46:47]
	v_pk_mul_f32 v[40:41], v[40:41], v[44:45]
	v_mul_f32_e32 v44, 0xbfb8aa3b, v36
	v_mul_f32_e32 v45, 0xbfb8aa3b, v37
	v_mul_f32_e32 v46, 0xbfb8aa3b, v38
	v_mul_f32_e32 v47, 0xbfb8aa3b, v39
	v_add_u32_e32 v68, 0x80, v150
	v_exp_f32_e32 v44, v44
	v_exp_f32_e32 v46, v46
	v_exp_f32_e32 v47, v47
	v_exp_f32_e32 v45, v45
	v_pk_mul_f32 v[58:59], v[58:59], v[64:65]
	v_cvt_pk_bf16_f32 v50, v52, v53
	v_mad_i64_i32 v[52:53], s[22:23], v68, s46, v[112:113]
	v_cvt_pk_bf16_f32 v49, v58, v59
	v_lshl_add_u64 v[52:53], v[52:53], 0, v[114:115]
	global_store_dwordx4 v[52:53], v[48:51], off
	v_exp_f32_e32 v56, v56
	v_exp_f32_e32 v57, v57
	v_pk_add_f32 v[50:51], v[54:55], 1.0 op_sel_hi:[1,0]
	v_pk_add_f32 v[46:47], v[46:47], 1.0 op_sel_hi:[1,0]
	v_rcp_f32_e32 v50, v50
	v_rcp_f32_e32 v51, v51
	v_pk_add_f32 v[44:45], v[44:45], 1.0 op_sel_hi:[1,0]
	v_rcp_f32_e32 v46, v46
	v_rcp_f32_e32 v44, v44
	v_rcp_f32_e32 v45, v45
	v_rcp_f32_e32 v47, v47
	v_pk_add_f32 v[48:49], v[56:57], 1.0 op_sel_hi:[1,0]
	v_pk_mul_f32 v[40:41], v[40:41], v[50:51]
	v_pk_mul_f32 v[34:35], v[34:35], v[38:39]
	v_pk_mul_f32 v[32:33], v[32:33], v[36:37]
	v_rcp_f32_e32 v48, v48
	v_rcp_f32_e32 v49, v49
	v_pk_mul_f32 v[36:37], v[32:33], v[44:45]
	v_pk_mul_f32 v[38:39], v[34:35], v[46:47]
	v_cvt_pk_bf16_f32 v32, v40, v41
	v_mul_f32_e32 v40, 0xbfb8aa3b, v30
	v_mul_f32_e32 v41, 0xbfb8aa3b, v31
	v_pk_mul_f32 v[26:27], v[26:27], v[30:31]
	v_mul_f32_e32 v30, 0xbfb8aa3b, v22
	v_mul_f32_e32 v31, 0xbfb8aa3b, v23
	v_cvt_pk_bf16_f32 v35, v38, v39
	v_mul_f32_e32 v38, 0xbfb8aa3b, v28
	v_mul_f32_e32 v39, 0xbfb8aa3b, v29
	v_exp_f32_e32 v30, v30
	v_exp_f32_e32 v31, v31
	v_exp_f32_e32 v38, v38
	v_exp_f32_e32 v39, v39
	v_pk_mul_f32 v[24:25], v[24:25], v[28:29]
	v_mul_f32_e32 v28, 0xbfb8aa3b, v20
	v_mul_f32_e32 v29, 0xbfb8aa3b, v21
	v_cvt_pk_bf16_f32 v34, v36, v37
	v_add_u32_e32 v36, 0x90, v150
	v_exp_f32_e32 v28, v28
	v_exp_f32_e32 v29, v29
	v_pk_mul_f32 v[42:43], v[42:43], v[48:49]
	v_mad_i64_i32 v[36:37], s[22:23], v36, s46, v[112:113]
	v_cvt_pk_bf16_f32 v33, v42, v43
	v_lshl_add_u64 v[36:37], v[36:37], 0, v[114:115]
	v_pk_add_f32 v[30:31], v[30:31], 1.0 op_sel_hi:[1,0]
	global_store_dwordx4 v[36:37], v[32:35], off
	v_rcp_f32_e32 v30, v30
	v_rcp_f32_e32 v31, v31
	v_pk_add_f32 v[34:35], v[38:39], 1.0 op_sel_hi:[1,0]
	v_exp_f32_e32 v40, v40
	v_exp_f32_e32 v41, v41
	v_rcp_f32_e32 v34, v34
	v_rcp_f32_e32 v35, v35
	v_pk_add_f32 v[28:29], v[28:29], 1.0 op_sel_hi:[1,0]
	v_pk_mul_f32 v[18:19], v[18:19], v[22:23]
	v_rcp_f32_e32 v28, v28
	v_rcp_f32_e32 v29, v29
	v_pk_mul_f32 v[22:23], v[18:19], v[30:31]
	v_pk_add_f32 v[32:33], v[40:41], 1.0 op_sel_hi:[1,0]
	v_pk_mul_f32 v[24:25], v[24:25], v[34:35]
	v_pk_mul_f32 v[16:17], v[16:17], v[20:21]
	v_cvt_pk_bf16_f32 v19, v22, v23
	v_mul_f32_e32 v22, 0xbfb8aa3b, v12
	v_mul_f32_e32 v23, 0xbfb8aa3b, v13
	v_pk_mul_f32 v[8:9], v[8:9], v[12:13]
	v_mul_f32_e32 v12, 0xbfb8aa3b, v4
	v_mul_f32_e32 v13, 0xbfb8aa3b, v5
	v_rcp_f32_e32 v32, v32
	v_rcp_f32_e32 v33, v33
	v_pk_mul_f32 v[20:21], v[16:17], v[28:29]
	v_cvt_pk_bf16_f32 v16, v24, v25
	v_mul_f32_e32 v24, 0xbfb8aa3b, v14
	v_mul_f32_e32 v25, 0xbfb8aa3b, v15
	v_pk_mul_f32 v[10:11], v[10:11], v[14:15]
	v_exp_f32_e32 v12, v12
	v_mul_f32_e32 v14, 0xbfb8aa3b, v6
	v_mul_f32_e32 v15, 0xbfb8aa3b, v7
	v_exp_f32_e32 v13, v13
	v_exp_f32_e32 v14, v14
	v_exp_f32_e32 v15, v15
	v_exp_f32_e32 v22, v22
	v_exp_f32_e32 v24, v24
	v_exp_f32_e32 v25, v25
	v_exp_f32_e32 v23, v23
	v_cvt_pk_bf16_f32 v18, v20, v21
	v_add_u32_e32 v20, 0xa0, v150
	v_pk_mul_f32 v[26:27], v[26:27], v[32:33]
	v_mad_i64_i32 v[20:21], s[22:23], v20, s46, v[112:113]
	v_pk_add_f32 v[12:13], v[12:13], 1.0 op_sel_hi:[1,0]
	v_cvt_pk_bf16_f32 v17, v26, v27
	v_lshl_add_u64 v[20:21], v[20:21], 0, v[114:115]
	v_pk_add_f32 v[14:15], v[14:15], 1.0 op_sel_hi:[1,0]
	v_rcp_f32_e32 v12, v12
	v_rcp_f32_e32 v13, v13
	global_store_dwordx4 v[20:21], v[16:19], off
	v_rcp_f32_e32 v14, v14
	v_rcp_f32_e32 v15, v15
	v_pk_add_f32 v[16:17], v[24:25], 1.0 op_sel_hi:[1,0]
	v_pk_add_f32 v[18:19], v[22:23], 1.0 op_sel_hi:[1,0]
	v_rcp_f32_e32 v16, v16
	v_rcp_f32_e32 v18, v18
	v_rcp_f32_e32 v19, v19
	v_rcp_f32_e32 v17, v17
	v_pk_mul_f32 v[0:1], v[0:1], v[4:5]
	v_pk_mul_f32 v[2:3], v[2:3], v[6:7]
	v_pk_mul_f32 v[4:5], v[0:1], v[12:13]
	v_pk_mul_f32 v[6:7], v[2:3], v[14:15]
	v_cvt_pk_bf16_f32 v2, v4, v5
	v_add_u32_e32 v4, 0xb0, v150
	v_pk_mul_f32 v[8:9], v[8:9], v[18:19]
	v_pk_mul_f32 v[10:11], v[10:11], v[16:17]
	v_mad_i64_i32 v[4:5], s[22:23], v4, s46, v[112:113]
	v_cvt_pk_bf16_f32 v0, v8, v9
	v_cvt_pk_bf16_f32 v1, v10, v11
	v_cvt_pk_bf16_f32 v3, v6, v7
	v_lshl_add_u64 v[4:5], v[4:5], 0, v[114:115]
	s_and_b64 vcc, exec, s[6:7]
	s_mov_b32 s47, s12
	s_mov_b32 s20, s14
	s_mov_b64 s[24:25], s[18:19]
	s_mov_b64 s[22:23], s[16:17]
	global_store_dwordx4 v[4:5], v[0:3], off
	s_cbranch_vccz .LBB0_1840
	s_waitcnt vmcnt(0)
	s_cmpk_gt_u32 s3, 0xff
	s_cbranch_scc1 .LBB0_1847
	s_barrier
